# speedup vs baseline: 1.0043x; 1.0043x over previous
; __device__ __forceinline__ KArgs kargs() { KArgs p = (KArgs)__builtin_amdgcn_kernarg_segment_ptr(); asm volatile("" : "+s"(p)); return p; }
; #define XBAR() do { KArgs kb_ = kargs(); xcd_barrier((unsigned*)(kb_->ws + WS_BAR), (volatile LAS unsigned*)(lds + LDS_BAR_OFF)); } while (0)
;     __host__ __device__ bool next(int i, Unit& u) const {
;         const long L = (long)i * G + c; if (L >= nwg) return false;
;         int wgid = (int)L; { const int q = nwg / NXCD, r = nwg % NXCD, xcd = wgid % NXCD, off = wgid / NXCD; wgid = (xcd < r ? xcd * (q + 1) : r * (q + 1) + (xcd - r) * q) + off; }
;         const int nig = WGM * nN, gid = wgid / nig, fm = gid * WGM, gsz = (nM - fm) < WGM ? (nM - fm) : WGM;
;         u.pm = fm + ((wgid % nig) % gsz); u.pn = (wgid % nig) / gsz; return true;
; __global__ void __launch_bounds__(NTHR, 2) fwd_megakernel(Args a_unused) {
;     ...
;     const bool defer = (G == 256);
;     prologue(lds, bid, G, threadIdx.x, defer);
;     if (gridDim.y == 0x7fffffffu) grid.sync();
;     XBAR();
; #pragma unroll 1
;     for (int l = 0; l < DEPTH; ++l) {
; #pragma unroll 1
;         for (int f = 0; f < 2; ++f) {
; #pragma unroll 1
;             for (int rep = 0; rep < (EXP_GU ? 2 : 1); ++rep) {
;                 KArgs ka = kargs(); unsigned char* ws = ka->ws; unsigned char* wl = ws + (size_t)l * WL_SIZE;
;                 pg8::Gemm g{f == 0 ? WSP(u16, WS_HBP) : WSP(u16, WS_HB), (const u16*)(wl + (f == 0 ? O_GU1 : O_GU2)), M, NGU, D}; pg8::StaticOrder S; S.init(M, NGU, G, bid);
;                 PrepRstd<16> P{lds, f == 0 ? WSP(float, WS_PART0) : WSP(float, WS_PART1), 1.0f / D};
;                 EpiGU E{WSP(u16, WS_ACT), lds};
;                 pg8::gemm_phase<EpiGU, PrepRstd<16>>(lds, g, S, E, P);
;                 if (defer && l + 1 < DEPTH && bid >= 128) convert_layer(lds, l + 1, f, 2, bid - 128, 128, threadIdx.x);
.LBB0_191:
	v_writelane_b32 v254, s15, 28
	v_writelane_b32 v254, s14, 29
	s_nop 1
	v_writelane_b32 v254, s15, 30
	s_or_b64 exec, exec, s[6:7]
	s_cmpk_lt_i32 s2, 0x580
	s_cselect_b64 s[0:1], -1, 0
	v_writelane_b32 v254, s0, 16
	s_add_i32 s6, s2, 0xffffff80
	s_ashr_i32 s7, s6, 31
	v_writelane_b32 v254, s1, 17
	s_lshr_b32 s0, s3, 29
	s_add_i32 s0, s2, s0
	s_ashr_i32 s12, s0, 3
	s_and_b32 s0, s0, -8
	s_sub_i32 s10, s2, s0
	s_lshl_b32 s0, s6, 3
	v_writelane_b32 v254, s0, 0
	s_lshl_b64 s[0:1], s[6:7], 9
	v_writelane_b32 v254, s0, 31
	s_cmpk_lt_i32 s2, 0x100
	s_waitcnt lgkmcnt(0)
	v_writelane_b32 v254, s1, 32
	s_cselect_b64 s[0:1], -1, 0
	s_lshl_b32 s11, s10, 5
	s_barrier
; __device__ __forceinline__ KArgs kargs() { KArgs p = (KArgs)__builtin_amdgcn_kernarg_segment_ptr(); asm volatile("" : "+s"(p)); return p; }
;     __host__ __device__ bool next(int i, Unit& u) const {
;         const long L = (long)i * G + c; if (L >= nwg) return false;
;         int wgid = (int)L; { const int q = nwg / NXCD, r = nwg % NXCD, xcd = wgid % NXCD, off = wgid / NXCD; wgid = (xcd < r ? xcd * (q + 1) : r * (q + 1) + (xcd - r) * q) + off; }
;         const int nig = WGM * nN, gid = wgid / nig, fm = gid * WGM, gsz = (nM - fm) < WGM ? (nM - fm) : WGM;
;         u.pm = fm + ((wgid % nig) % gsz); u.pn = (wgid % nig) / gsz; return true;
; __global__ void __launch_bounds__(NTHR, 2) fwd_megakernel(Args a_unused) {
;     ...
;     for (int l = 0; l < DEPTH; ++l) {
; #pragma unroll 1
;         for (int f = 0; f < 2; ++f) {
; #pragma unroll 1
;             for (int rep = 0; rep < (EXP_GU ? 2 : 1); ++rep) {
;                 KArgs ka = kargs(); unsigned char* ws = ka->ws; unsigned char* wl = ws + (size_t)l * WL_SIZE;
;                 pg8::Gemm g{f == 0 ? WSP(u16, WS_HBP) : WSP(u16, WS_HB), (const u16*)(wl + (f == 0 ? O_GU1 : O_GU2)), M, NGU, D}; pg8::StaticOrder S; S.init(M, NGU, G, bid);
;                 PrepRstd<16> P{lds, f == 0 ? WSP(float, WS_PART0) : WSP(float, WS_PART1), 1.0f / D};
;                 EpiGU E{WSP(u16, WS_ACT), lds};
;                 pg8::gemm_phase<EpiGU, PrepRstd<16>>(lds, g, S, E, P);
;                 if (defer && l + 1 < DEPTH && bid >= 128) convert_layer(lds, l + 1, f, 2, bid - 128, 128, threadIdx.x);
	s_load_dwordx2 s[100:101], s[40:41], 0x100
	v_and_b32_e32 v2, 63, v234
	v_lshlrev_b32_e32 v2, 4, v2
	v_and_b32_e32 v3, 16, v2
	v_add_u32_e32 v2, 0x12b93600, v2
	v_add_u32_e32 v3, 0x12b93600, v3
	s_waitcnt lgkmcnt(0)
	global_load_dwordx4 v[4:7], v2, s[100:101] sc1
	global_load_dwordx4 v[12:15], v3, s[100:101] sc1
	s_waitcnt vmcnt(0)
	v_xor_b32_e32 v12, v12, v4
	v_xor_b32_e32 v13, v13, v5
	v_xor_b32_e32 v14, v14, v6
	v_xor_b32_e32 v15, v15, v7
	v_or3_b32 v12, v12, v13, v14
	v_or_b32_e32 v12, v12, v15
	v_min_u32_e32 v4, v4, v5
	v_min3_u32 v4, v4, v6, v7
	v_cmp_ne_u32_e64 s[98:99], 0, v12
	v_cmp_eq_u32_e32 vcc, 0, v4
	s_nop 4
	s_or_b64 s[98:99], s[98:99], vcc
	s_cmp_eq_u64 s[98:99], 0
	s_cselect_b32 s98, 1, 0
	v_writelane_b32 v254, s0, 6
	s_cmpk_lt_i32 s2, 0x200
	s_load_dwordx2 s[14:15], s[40:41], 0x108
	v_writelane_b32 v254, s1, 7
	s_cselect_b64 s[0:1], -1, 0
	s_lshl_b32 s13, s10, 6
	v_writelane_b32 v254, s0, 33
	s_cmpk_lt_i32 s2, 0x80
	s_movk_i32 s33, 0xb1
	v_writelane_b32 v254, s1, 34
	s_cselect_b64 s[0:1], -1, 0
	v_writelane_b32 v254, s0, 35
	s_lshl_b32 s16, s10, 4
	s_waitcnt lgkmcnt(0)
	s_mul_i32 s15, s15, s14
	v_writelane_b32 v254, s1, 36
	s_lshr_b32 s0, s14, 31
	s_add_i32 s0, s14, s0
	s_ashr_i32 s0, s0, 1
	s_add_i32 s17, s0, s2
	s_cmpk_gt_i32 s2, 0x7f
	s_cselect_b64 s[8:9], -1, 0
	s_and_b64 s[0:1], s[8:9], exec
	s_cselect_b32 s0, 0x80, 1
	v_writelane_b32 v254, s0, 37
	s_cselect_b32 s0, s6, 0x100000
	v_writelane_b32 v254, s0, 38
	s_load_dword s0, s[40:41], 0x110
	s_cmp_lt_i32 s10, 0
	s_cselect_b32 s21, s33, 0xb0
	s_mul_i32 s1, s10, 0x41
	s_mul_i32 s20, s10, 17
	s_waitcnt lgkmcnt(0)
	s_mul_i32 s15, s15, s0
	s_mul_i32 s0, s10, 33
	s_mul_i32 s10, s10, s21
	s_cselect_b32 s11, s0, s11
	s_cselect_b32 s13, s1, s13
	s_cselect_b32 s16, s20, s16
	s_add_i32 s10, s10, s12
	s_mul_hi_i32 s0, s10, 0x2e8ba2e9
	s_lshr_b32 s1, s0, 31
	s_ashr_i32 s0, s0, 4
	s_add_i32 s0, s0, s1
	s_mul_i32 s1, s0, 0x58
	s_sub_i32 s1, s10, s1
	s_lshl_b32 s20, s0, 2
	s_bfe_i32 s0, s1, 0x80000
	s_bfe_u32 s0, s0, 0x2000d
	s_add_i32 s10, s1, s0
	s_bfe_i32 s0, s10, 0x80000
	s_and_b32 s10, s10, 0xfc
	s_sub_i32 s1, s1, s10
	s_sext_i32_i16 s21, s0
	s_sext_i32_i8 s1, s1
	s_add_i32 s20, s20, s1
	s_ashr_i32 s1, s21, 2
	v_writelane_b32 v254, s1, 39
	s_mov_b32 s10, s20
	s_lshr_b32 s0, s21, 2
	s_ashr_i32 s21, s20, 31
	v_writelane_b32 v254, s10, 40
	s_lshl_b64 s[20:21], s[20:21], 19
	s_bfe_i64 s[0:1], s[0:1], 0x100000
	v_writelane_b32 v254, s11, 41
	v_writelane_b32 v254, s20, 42
	s_lshl_b64 s[0:1], s[0:1], 19
	s_and_b64 s[8:9], s[66:67], s[8:9]
	v_writelane_b32 v254, s21, 43
	v_writelane_b32 v254, s0, 44
	s_mov_b32 s63, 0
	v_mov_b32_e32 v1, 0
	v_writelane_b32 v254, s1, 45
	s_add_i32 s0, s11, s12
	s_ashr_i32 s1, s0, 31
	s_lshr_b32 s1, s1, 28
	s_add_i32 s1, s0, s1
	s_ashr_i32 s10, s1, 4
	s_and_b32 s1, s1, 0xfff0
	s_sub_i32 s1, s0, s1
	s_bfe_i32 s0, s1, 0x80000
	s_bfe_u32 s0, s0, 0x2000d
	s_add_i32 s11, s1, s0
	s_bfe_i32 s0, s11, 0x80000
	s_and_b32 s11, s11, 0xfc
	s_sub_i32 s1, s1, s11
	s_lshl_b32 s10, s10, 2
	s_sext_i32_i16 s20, s0
	s_sext_i32_i8 s1, s1
	s_add_i32 s22, s10, s1
	s_ashr_i32 s1, s20, 2
	v_writelane_b32 v254, s1, 10
	s_add_i32 s1, s13, s12
	s_ashr_i32 s10, s1, 31
	s_lshr_b32 s10, s10, 27
	s_add_i32 s10, s1, s10
	s_ashr_i32 s11, s10, 5
	s_and_b32 s10, s10, 0xffe0
	s_sub_i32 s1, s1, s10
	s_bfe_i32 s10, s1, 0x80000
	s_bfe_u32 s10, s10, 0x2000d
	s_add_i32 s13, s1, s10
	s_bfe_i32 s10, s13, 0x80000
	s_and_b32 s13, s13, 0xfc
	s_sub_i32 s1, s1, s13
	s_lshr_b32 s0, s20, 2
	s_lshl_b32 s11, s11, 2
	s_sext_i32_i16 s20, s10
	s_sext_i32_i8 s1, s1
	s_add_i32 s24, s11, s1
	s_ashr_i32 s1, s20, 2
	s_lshr_b32 s10, s20, 2
	v_writelane_b32 v254, s1, 46
	s_mov_b32 s20, s24
	s_ashr_i32 s25, s24, 31
	v_writelane_b32 v254, s20, 47
	s_bfe_i64 s[10:11], s[10:11], 0x100000
	s_lshl_b64 s[10:11], s[10:11], 19
	v_writelane_b32 v254, s21, 48
	s_lshl_b64 s[20:21], s[24:25], 19
	v_writelane_b32 v254, s20, 49
	s_add_i32 s1, s16, s12
	s_ashr_i32 s23, s22, 31
	v_writelane_b32 v254, s21, 50
	v_writelane_b32 v254, s10, 51
	v_mov_b32_e32 v230, 0x358637bd
	s_mov_b32 s35, 0x800000
	v_writelane_b32 v254, s11, 52
	s_ashr_i32 s10, s1, 31
	s_lshr_b32 s10, s10, 29
	s_add_i32 s10, s1, s10
	s_ashr_i32 s11, s10, 3
	s_and_b32 s10, s10, 0xfff8
	s_sub_i32 s1, s1, s10
	s_bfe_i32 s10, s1, 0x80000
	s_bfe_u32 s10, s10, 0x2000d
	s_add_i32 s12, s1, s10
	s_bfe_i32 s10, s12, 0x80000
	s_and_b32 s12, s12, 0xfc
	s_sub_i32 s1, s1, s12
	s_lshl_b32 s11, s11, 2
	s_sext_i32_i16 s13, s10
	s_sext_i32_i8 s1, s1
	s_add_i32 s20, s11, s1
	s_ashr_i32 s1, s13, 2
	v_writelane_b32 v254, s1, 53
	v_writelane_b32 v254, s8, 54
	s_mov_b32 s12, s22
	s_lshr_b32 s10, s13, 2
	v_writelane_b32 v254, s9, 55
	s_abs_i32 s8, s14
	v_cvt_f32_u32_e32 v0, s8
	v_writelane_b32 v254, s12, 8
	s_bfe_i64 s[0:1], s[0:1], 0x100000
	s_lshl_b64 s[0:1], s[0:1], 19
	v_rcp_iflag_f32_e32 v0, v0
	v_writelane_b32 v254, s13, 9
	s_lshl_b64 s[12:13], s[22:23], 19
	v_writelane_b32 v254, s12, 56
	v_mul_f32_e32 v0, 0x4f7ffffe, v0
	v_cvt_u32_f32_e32 v0, v0
	v_writelane_b32 v254, s13, 57
	v_writelane_b32 v254, s0, 58
	s_ashr_i32 s21, s20, 31
	s_sub_i32 s9, 0, s8
	v_writelane_b32 v254, s1, 59
	s_mov_b32 s0, s20
	v_writelane_b32 v254, s0, 60
	s_mov_b32 s22, 0x10000
	s_mov_b32 s23, 0x16000
	v_writelane_b32 v254, s1, 61
	s_lshl_b64 s[0:1], s[20:21], 13
	v_writelane_b32 v254, s0, 62
	s_movk_i32 s37, 0x1600
	s_mov_b32 s50, 0x26000
	v_writelane_b32 v254, s1, 63
	s_bfe_i64 s[0:1], s[10:11], 0x100000
	v_readfirstlane_b32 s10, v0
	s_lshl_b64 s[0:1], s[0:1], 18
	s_mul_i32 s9, s9, s10
	v_writelane_b32 v255, s0, 0
	s_mul_hi_u32 s9, s10, s9
	s_add_i32 s10, s10, s9
	v_writelane_b32 v255, s1, 1
	s_abs_i32 s1, s17
	s_mul_hi_u32 s9, s1, s10
	s_mul_i32 s9, s9, s8
	s_sub_i32 s1, s1, s9
	s_ashr_i32 s0, s17, 31
	s_sub_i32 s9, s1, s8
	s_cmp_ge_u32 s1, s8
	s_cselect_b32 s1, s9, s1
	s_sub_i32 s9, s1, s8
	s_cmp_ge_u32 s1, s8
	s_cselect_b32 s1, s9, s1
	s_xor_b32 s1, s1, s0
	s_sub_i32 s0, s1, s0
	v_writelane_b32 v255, s0, 2
	s_lshl_b64 s[0:1], s[6:7], 13
	v_writelane_b32 v255, s0, 3
	s_lshl_b32 s39, s14, 2
	v_mov_b64_e32 v[232:233], 0x57f
	v_writelane_b32 v255, s1, 4
	s_lshl_b64 s[0:1], s[6:7], 14
	v_writelane_b32 v255, s0, 5
	v_mov_b64_e32 v[236:237], 0x580
	v_mov_b64_e32 v[240:241], 0x100
	v_writelane_b32 v255, s1, 6
	s_lshl_b32 s0, s2, 2
	v_writelane_b32 v255, s0, 7
	s_add_i32 s0, 0, 0x20000
	v_writelane_b32 v254, s0, 12
	s_add_i32 s0, 0, 0x23ff0
	v_writelane_b32 v254, s0, 26
	s_add_i32 s0, 0, 0x23ff4
	v_mov_b64_e32 v[242:243], 0xff
	v_mbcnt_hi_u32_b32 v231, -1, v42
	v_mov_b64_e32 v[244:245], 0x1ff
	s_mov_b32 s51, 0x2c000
	s_mov_b32 s52, 0x3c000
	s_movk_i32 s38, 0x5000
	s_mov_b32 s36, 0xb000
	s_mov_b32 s53, 0x1b000
	v_writelane_b32 v254, s0, 24
	s_add_i32 s34, 0, 0x11100
	s_mov_b64 s[64:65], 0x40000
	s_mov_b64 s[66:67], 0x80
	s_mov_b64 s[68:69], 0x100
	s_mov_b64 s[72:73], 0x200000
	s_mov_b64 s[74:75], 0x800000
	s_mov_b64 s[80:81], 0x180
	s_mov_b32 s82, s63
	s_branch .LBB0_193

; #define PG8_STAGE(bufoff, gbase, voff) do { _Pragma("unroll") for (int _i = 0; _i < 2; ++_i) \
;         __builtin_amdgcn_global_load_lds((const unsigned*)((const char*)(gbase) + (voff)[_i]), (LAS unsigned*)(lds + (bufoff) + ldsw + _i * 8192), 16, 0, 0); } while (0)
; #define PG8_BAR __builtin_amdgcn_s_barrier()
; template <class Epi, class Pre, bool AG = false>
; __device__ __forceinline__ void gemm_phase(LAS unsigned char* lds, const Gemm g, const StaticOrder& S, const Epi& E, const Pre& P) {
;     ...
;     const int tid = tid_, wid = __builtin_amdgcn_readfirstlane(tid >> 6), lane = tid & 63, wr = wid >> 2, wc = wid & 3, fr = lane & 15, fq = lane >> 4;
;     const int K = g.K, nt = K / BK;
;     unsigned voffA[2], voffB[2];
; #pragma unroll
;     for (int i = 0; i < 2; ++i) { int R, C; stage_rc(tid * 16 + i * 8192, R, C); const int Rb = Epi::PERM ? ((R & ~31) + perm32(R & 31)) : R;
;         voffA[i] = AG ? (unsigned)((C >> 4) * g.M * 16 + R * 16 + (C & 15)) * 2u : (unsigned)(R * K + C) * 2u; voffB[i] = (unsigned)(Rb * K + C) * 2u; }
;     const size_t kstep = (size_t)(BK * 2), kstepA = AG ? (size_t)(BK / 16) * g.M * 32 : kstep;
;     const size_t hstep = (size_t)HALF * K * 2, hstepA = AG ? (size_t)HALF * 32 : hstep;
;     const size_t tstep = 2 * hstep, tstepA = 2 * hstepA;
;     const unsigned ldsw = (unsigned)wid * 1024u;
;     const int aoff = lds_byte(wr * 64 + fr, fq * 8), boff = lds_byte(wc * 32 + fr, fq * 8);
;     ...
;     Unit cur, nxt; int ui = 0;
;     if (!S.next(0, cur)) return;
;     f32x4 acc[2][2][4][2];
; #pragma unroll
;     for (int a = 0; a < 2; ++a)
; #pragma unroll
;         for (int b = 0; b < 2; ++b)
; #pragma unroll
;             for (int m = 0; m < 4; ++m)
; #pragma unroll
;                 for (int n = 0; n < 2; ++n) acc[a][b][m][n] = (f32x4){0.f, 0.f, 0.f, 0.f};
;     bf16x8 At[4][2], B0[2][2], B1[2][2];
;     const char* cA = (const char*)g.A + (size_t)cur.pm * tstepA; const char* cB = (const char*)g.Bt + (size_t)cur.pn * tstep;
;     PG8_STAGE(PG8_SB(0, 0), cB, voffB); PG8_STAGE(PG8_SB(0, 1), cB + hstep, voffB); PG8_STAGE(PG8_SA(0, 0), cA, voffA); PG8_STAGE(PG8_SA(0, 1), cA + hstepA, voffA);
;     P(S);
;     if (wr == 1) PG8_BAR;
;     PG8_WAIT_V(2); PG8_BAR;
;     PG8_STAGE(PG8_SB(1, 0), cB + kstep, voffB); PG8_STAGE(PG8_SA(1, 0), cA + kstepA, voffA); PG8_STAGE(PG8_SB(1, 1), cB + hstep + kstep, voffB);
;     PG8_WAIT_V(6); PG8_BAR;
.LBB0_197:
	v_readlane_b32 s6, v254, 16
	s_mov_b64 s[0:1], s[40:41]
	v_mov_b32_e32 v15, v234
	v_readlane_b32 s7, v254, 17
	s_and_b64 vcc, exec, s[6:7]
	v_readfirstlane_b32 s16, v15
	s_cbranch_vccz .LBB0_219
	v_lshlrev_b32_e32 v0, 4, v15
	v_add_u32_e32 v2, 0x2000, v0
	v_ashrrev_i32_e32 v3, 31, v2
	v_lshrrev_b32_e32 v3, 22, v3
	s_mov_b64 s[8:9], s[100:101]
	v_add_u32_e32 v3, v2, v3
	v_ashrrev_i32_e32 v10, 10, v3
	v_mul_i32_i24_e32 v3, 0x400, v10
	s_and_b64 s[0:1], s[94:95], exec
	v_sub_u32_e32 v2, v2, v3
	s_mov_b32 s0, 0xe910000
	s_mov_b32 s6, 0x12910000
	v_readlane_b32 s7, v254, 20
	v_lshrrev_b32_e32 v3, 4, v2
	s_cselect_b32 s0, s0, 0xc910000
	s_cselect_b32 s1, 0, 0x1700000
	s_cselect_b32 s6, s6, 0x12a10000
	s_waitcnt lgkmcnt(0)
	s_add_u32 s7, s8, s7
	v_bitop3_b32 v2, v3, v2, 32 bitop3:0x6c
	s_addc_u32 s10, s9, 0
	v_ashrrev_i32_e32 v3, 31, v2
	s_add_u32 s20, s8, s0
	v_lshrrev_b32_e32 v3, 26, v3
	s_addc_u32 s24, s9, 0
	v_add_u32_e32 v3, v2, v3
	v_lshlrev_b32_e32 v4, 3, v10
	s_add_u32 s25, s7, s1
	v_ashrrev_i32_e32 v11, 6, v3
	v_and_b32_e32 v4, -16, v4
	s_addc_u32 s30, s10, 0
	v_add_u32_e32 v4, v11, v4
	s_add_u32 s0, s8, s6
	v_and_b32_e32 v5, 3, v11
	s_mov_b32 s6, 0x1fffe0
	v_lshrrev_b32_e32 v6, 2, v4
	v_lshlrev_b32_e32 v7, 1, v4
	v_and_b32_e32 v3, 0xc0, v3
	v_and_or_b32 v5, v4, s6, v5
	v_and_b32_e32 v6, 4, v6
	v_and_b32_e32 v7, 24, v7
	v_sub_u32_e32 v2, v2, v3
	v_mov_b32_e32 v8, 1
	v_or3_b32 v5, v5, v6, v7
	v_lshlrev_b32_e32 v6, 5, v10
	v_ashrrev_i16_sdwa v2, v8, sext(v2) dst_sel:DWORD dst_unused:UNUSED_PAD src0_sel:DWORD src1_sel:BYTE_0
	v_and_b32_e32 v6, 32, v6
	v_bfe_i32 v12, v2, 0, 16
	v_add_lshl_u32 v2, v6, v12, 1
	v_lshl_add_u32 v130, v5, 11, v2
	v_lshl_add_u32 v132, v4, 11, v2
	v_bfe_i32 v2, v15, 27, 1
	v_lshrrev_b32_e32 v2, 22, v2
	v_add_u32_e32 v2, v0, v2
	v_and_b32_e32 v2, 0xfffffc00, v2
	v_sub_u32_e32 v0, v0, v2
	v_lshrrev_b32_e32 v2, 4, v0
	v_ashrrev_i32_e32 v4, 31, v15
	v_bitop3_b32 v2, v2, v0, 32 bitop3:0x6c
	v_lshrrev_b32_e32 v4, 26, v4
	v_ashrrev_i32_e32 v0, 31, v2
	v_add_u32_e32 v4, v15, v4
	v_lshrrev_b32_e32 v0, 26, v0
	v_ashrrev_i32_e32 v13, 6, v4
	v_add_u32_e32 v3, v2, v0
	v_lshlrev_b32_e32 v4, 3, v13
	v_ashrrev_i32_e32 v0, 6, v3
	v_and_b32_e32 v4, -16, v4
	v_add_u32_e32 v4, v0, v4
	v_and_b32_e32 v5, 3, v0
	v_lshrrev_b32_e32 v6, 2, v4
	v_lshlrev_b32_e32 v7, 1, v4
	v_and_b32_e32 v3, 0xc0, v3
	s_addc_u32 s1, s9, 0
	s_ashr_i32 s17, s16, 6
	v_and_or_b32 v5, v4, s6, v5
	v_and_b32_e32 v6, 4, v6
	v_and_b32_e32 v7, 24, v7
	v_sub_u32_e32 v2, v2, v3
	s_lshl_b32 s31, s17, 10
	v_or3_b32 v5, v5, v6, v7
	v_lshlrev_b32_e32 v6, 5, v13
	v_ashrrev_i16_sdwa v2, v8, sext(v2) dst_sel:DWORD dst_unused:UNUSED_PAD src0_sel:DWORD src1_sel:BYTE_0
	v_readlane_b32 s6, v254, 44
	v_and_b32_e32 v6, 32, v6
	v_bfe_i32 v14, v2, 0, 16
	v_readlane_b32 s7, v254, 45
	s_add_u32 s46, s25, s6
	v_add_lshl_u32 v2, v6, v14, 1
	s_addc_u32 s47, s30, s7
	s_add_i32 s38, s31, 0
	v_lshl_add_u32 v134, v5, 11, v2
	s_add_i32 m0, s38, 0x10000
	v_lshl_add_u32 v136, v4, 11, v2
	global_load_lds_dwordx4 v134, s[46:47]
	s_add_i32 m0, s38, 0x12000
	s_add_u32 s6, s46, 0x40000
	global_load_lds_dwordx4 v130, s[46:47]
	s_addc_u32 s7, s47, 0
	s_add_i32 m0, s38, 0x14000
	v_mov_b32_e32 v135, v1
	global_load_lds_dwordx4 v134, s[6:7]
	s_add_i32 m0, s38, 0x16000
	v_mov_b32_e32 v131, v1
	global_load_lds_dwordx4 v130, s[6:7]
	v_readlane_b32 s6, v254, 42
	v_readlane_b32 s7, v254, 43
	s_add_u32 s44, s20, s6
	s_addc_u32 s45, s24, s7
	s_add_i32 s48, s38, 0x2000
	s_mov_b32 m0, s38
	s_add_u32 s6, s44, 0x40000
	global_load_lds_dwordx4 v136, s[44:45]
	s_mov_b32 m0, s48
	s_addc_u32 s7, s45, 0
	s_add_i32 s49, s38, 0x4000
	global_load_lds_dwordx4 v132, s[44:45]
	s_mov_b32 m0, s49
	s_add_i32 s53, s38, 0x6000
	global_load_lds_dwordx4 v136, s[6:7]
	s_mov_b32 m0, s53
	v_mov_b32_e32 v137, v1
	global_load_lds_dwordx4 v132, s[6:7]
	v_mov_b32_e32 v133, v1
	v_mov_b32_e32 v16, v234
	s_movk_i32 s6, 0x100
	v_readlane_b32 s10, v254, 12
	v_lshl_add_u64 v[8:9], s[46:47], 0, v[134:135]
	v_lshl_add_u64 v[6:7], s[46:47], 0, v[130:131]
	v_lshl_add_u64 v[4:5], s[44:45], 0, v[136:137]
	v_lshl_add_u64 v[2:3], s[44:45], 0, v[132:133]
	s_movk_i32 s26, 0xc400
	v_cmp_gt_i32_e64 s[6:7], s6, v16
	v_lshl_add_u32 v17, v16, 2, s10
	s_mov_b64 s[10:11], s[2:3]
	s_cmp_eq_u32 s18, 0x100
	s_cbranch_scc1 .Lpr_gu_begin
	s_branch .LBB0_201

; #define LAS __attribute__((address_space(3)))
; __device__ __forceinline__ KArgs kargs() { KArgs p = (KArgs)__builtin_amdgcn_kernarg_segment_ptr(); asm volatile("" : "+s"(p)); return p; }
; __device__ __forceinline__ void convert_layer(LAS unsigned char* lds, int l, int part, int nparts, int widx, int nworkers, int tid_in) {
;     int tid = tid_in; asm volatile("" : "+v"(tid));
;     KArgs ka = kargs();
;     ...
;     const int wave = __builtin_amdgcn_readfirstlane(tid >> 6), lane = tid & 63;
;     const int gw = widx * NWAVES + wave, NGW = nworkers * NWAVES;
;     unsigned char* ws = a.ws;
;     LAS float* scr = (LAS float*)(lds + wave * 16384);
;     constexpr int I_FFN = (D / 64) * (FF / 32), I_DN = (FF / 64) * (D / 32), I_IN = (D / 64) * (INC / 32), I_GL = (SWD / 64) * (SWD / 32), I_WO = (512 / 64) * (D / 32), I_G = (D / 64) * (D / 32), I_PP = (PLE / 64) * (D / 32);
;     constexpr int PER_LAYER = 4 * I_FFN + 2 * I_DN + I_IN + I_GL + 2 * I_WO + I_G + I_PP;
;     const int it_lo = (int)((long)PER_LAYER * part / nparts), it_hi = (int)((long)PER_LAYER * (part + 1) / nparts);
;     for (int it = it_lo + gw; it < it_hi; it += NGW) {
;         int r = it;
;         KArgs ka = kargs();
;         unsigned char* wl = a.ws + (size_t)l * WL_SIZE;
.LBB0_219:
	v_readlane_b32 s0, v254, 14
	v_readlane_b32 s1, v254, 15
	s_andn2_b64 vcc, exec, s[0:1]
	s_cbranch_vccnz .LBB0_310
	v_mov_b32_e32 v10, v234
	s_mov_b64 s[6:7], s[40:41]
	s_mul_i32 s0, s78, 0x1500
	v_readlane_b32 s1, v254, 0
	s_mov_b64 s[92:93], s[100:101]
	s_add_i32 s12, s0, 0x1500
	s_add_i32 s1, s0, s1
	v_readfirstlane_b32 s0, v10
	s_ashr_i32 s0, s0, 6
	s_add_i32 s13, s1, s0
	v_readlane_b32 s8, v254, 18
	s_cmp_ge_i32 s13, s12
	v_readlane_b32 s9, v254, 19
	s_cbranch_scc1 .LBB0_294
	s_lshl_b32 s0, s0, 14
	v_bfe_u32 v11, v10, 5, 1
	v_and_b32_e32 v12, 31, v10
	s_add_i32 s0, s0, 0
	v_and_b32_e32 v0, 7, v10
	v_lshlrev_b32_e32 v2, 2, v12
	v_mul_u32_u24_e32 v3, 0x84, v11
	v_bfe_u32 v15, v10, 3, 3
	v_lshlrev_b32_e32 v14, 3, v0
	v_add3_u32 v13, s0, v2, v3
	v_mul_u32_u24_e32 v0, 0x420, v0
	v_lshlrev_b32_e32 v2, 2, v15
	v_add3_u32 v18, s0, v0, v2
	v_or_b32_e32 v19, 8, v15
	v_or_b32_e32 v20, 16, v15
	v_or_b32_e32 v21, 24, v15
	s_lshl_b32 s16, s13, 5
	s_lshl_b32 s17, s13, 6
	s_lshl_b32 s26, s13, 1
	s_lshl_b32 s27, s13, 2
	s_branch .LBB0_225

;     const int nblk = N / 32, kb = item / nblk, nb = item % nblk, k0 = 64 * kb, n0 = 32 * nb;
;     float v[32];
;     const float* wp = W + (size_t)(k0 + (lane >> 5)) * N + n0 + (lane & 31);
; #pragma unroll
; __device__ __forceinline__ void convert_layer(LAS unsigned char* lds, int l, int part, int nparts, int widx, int nworkers, int tid_in) {
;     ...
;     for (int it = it_lo + gw; it < it_hi; it += NGW) {
;         int r = it;
;         KArgs ka = kargs();
;         unsigned char* wl = a.ws + (size_t)l * WL_SIZE;
;         if (r < I_FFN) { xpose_item(a.in[I_F1G] + (size_t)l * D * FF, D, FF, a.in[I_F1N] + l * D, (u16*)(wl + O_GU1), 1, scr, r, lane); continue; } r -= I_FFN;
;         if (r < I_FFN) { xpose_item(a.in[I_F1U] + (size_t)l * D * FF, D, FF, a.in[I_F1N] + l * D, (u16*)(wl + O_GU1), 2, scr, r, lane); continue; } r -= I_FFN;
;         if (r < I_DN) { xpose_item(a.in[I_F1D] + (size_t)l * FF * D, FF, D, nullptr, (u16*)(wl + O_D1), 0, scr, r, lane); continue; } r -= I_DN;
;         if (r < I_FFN) { xpose_item(a.in[I_F2G] + (size_t)l * D * FF, D, FF, a.in[I_F2N] + l * D, (u16*)(wl + O_GU2), 1, scr, r, lane); continue; } r -= I_FFN;
;         if (r < I_FFN) { xpose_item(a.in[I_F2U] + (size_t)l * D * FF, D, FF, a.in[I_F2N] + l * D, (u16*)(wl + O_GU2), 2, scr, r, lane); continue; } r -= I_FFN;
;         if (r < I_DN) { xpose_item(a.in[I_F2D] + (size_t)l * FF * D, FF, D, nullptr, (u16*)(wl + O_D2), 0, scr, r, lane); continue; } r -= I_DN;
;         if (r < I_IN) { xpose_item(a.in[I_WIN] + (size_t)l * D * INC, D, INC, a.in[I_MIXN] + l * D, (u16*)(wl + O_WIN), 0, scr, r, lane); continue; } r -= I_IN;
;         if (r < I_GL) { xpose_item(a.in[I_GLUW] + (size_t)l * SWD * SWD, SWD, SWD, nullptr, (u16*)(wl + O_GLU), 0, scr, r, lane); continue; } r -= I_GL;
;         if (r < 2 * I_WO) {
;             const int k0 = 64 * (r / (D / 32));
;             const float* gn = (k0 < 512) ? (a.in[I_CON] + l * 512) : (a.in[I_SON] + l * 512 - 512);
;             xpose_item(a.in[I_WOUT] + (size_t)l * D * D, D, D, gn, (u16*)(wl + O_WO), 0, scr, r, lane, 512); continue; } r -= 2 * I_WO;
;         if (r < I_G) { xpose_item(a.in[I_PLEG] + (size_t)l * D * D, D, D, a.in[I_PLEN] + l * D, (u16*)(wl + O_PG), 0, scr, r, lane); continue; } r -= I_G;
;         xpose_item(a.in[I_PLEP] + (size_t)l * PLE * D, PLE, D, nullptr, (u16*)(wl + O_PP), 0, scr, r, lane);
.LBB0_225:
	s_mov_b64 s[0:1], s[40:41]
	s_mov_b64 s[8:9], s[100:101]
	s_waitcnt lgkmcnt(0)
	s_add_u32 s29, s8, s96
	s_mul_hi_u32 s8, s82, 0x2a44000
	s_addc_u32 s28, s9, s8
	s_cmpk_gt_i32 s13, 0x57f
	s_mov_b64 s[8:9], -1
	s_cbranch_scc0 .LBB0_285
	s_cmpk_gt_u32 s13, 0xaff
	s_cbranch_scc0 .LBB0_279
	s_cmpk_gt_u32 s13, 0x107f
	s_cbranch_scc0 .LBB0_276
	s_cmpk_gt_u32 s13, 0x15ff
	s_cbranch_scc0 .LBB0_270
	s_cmpk_gt_u32 s13, 0x1b7f
	s_cbranch_scc0 .LBB0_264
	s_cmpk_gt_u32 s13, 0x20ff
	s_cbranch_scc0 .LBB0_261
	s_cmpk_gt_u32 s13, 0x24ff
	s_cbranch_scc0 .LBB0_255
	s_cmpk_gt_u32 s13, 0x257f
	s_cbranch_scc0 .LBB0_252
	s_cmpk_gt_u32 s13, 0x277f
	s_cbranch_scc0 .LBB0_242
	s_cmpk_gt_u32 s13, 0x297f
	s_cbranch_scc0 .LBB0_236
	s_load_dwordx2 s[8:9], s[0:1], 0xe8
	v_readlane_b32 s10, v255, 8
	v_readlane_b32 s11, v255, 9
	s_waitcnt lgkmcnt(0)
	s_add_u32 s24, s8, s10
	s_addc_u32 s25, s9, s11
	s_and_b32 s8, s26, 0x7fffffc0
	s_addk_i32 s8, 0xad00
	v_or_b32_e32 v0, s8, v11
	s_and_b32 s10, s16, 0x3e0
	v_lshlrev_b64 v[2:3], 12, v[0:1]
	v_lshl_add_u64 v[2:3], s[24:25], 0, v[2:3]
	s_lshl_b32 s62, s10, 2
	v_lshl_add_u64 v[2:3], v[2:3], 0, s[62:63]
	v_lshlrev_b32_e32 v0, 2, v12
	v_lshl_add_u64 v[2:3], v[2:3], 0, v[0:1]
	s_movk_i32 s9, 0x2000
	v_add_co_u32_e32 v4, vcc, s9, v2
	s_movk_i32 s9, 0x4000
	s_nop 0
	v_addc_co_u32_e32 v5, vcc, 0, v3, vcc
	global_load_dword v0, v[2:3], off nt
	global_load_dword v6, v[4:5], off nt
	v_add_co_u32_e32 v4, vcc, s9, v2
	s_movk_i32 s9, 0x6000
	s_nop 0
	v_addc_co_u32_e32 v5, vcc, 0, v3, vcc
	global_load_dword v7, v[4:5], off nt
	v_add_co_u32_e32 v4, vcc, s9, v2
	s_mov_b32 s9, 0x8000
	s_nop 0
	v_addc_co_u32_e32 v5, vcc, 0, v3, vcc
	global_load_dword v8, v[4:5], off nt
	v_add_co_u32_e32 v4, vcc, s9, v2
	s_mov_b32 s9, 0xa000
	s_nop 0
	v_addc_co_u32_e32 v5, vcc, 0, v3, vcc
	global_load_dword v9, v[4:5], off nt
	v_add_co_u32_e32 v4, vcc, s9, v2
	s_mov_b32 s9, 0xc000
	s_nop 0
	v_addc_co_u32_e32 v5, vcc, 0, v3, vcc
	global_load_dword v16, v[4:5], off nt
	v_add_co_u32_e32 v4, vcc, s9, v2
	s_mov_b32 s9, 0xe000
	s_nop 0
	v_addc_co_u32_e32 v5, vcc, 0, v3, vcc
	global_load_dword v17, v[4:5], off nt
	v_add_co_u32_e32 v4, vcc, s9, v2
	s_mov_b32 s9, 0x12000
	s_nop 0
	v_addc_co_u32_e32 v5, vcc, 0, v3, vcc
	global_load_dword v22, v[4:5], off nt
	v_add_co_u32_e32 v4, vcc, s22, v2
	s_nop 1
	v_addc_co_u32_e32 v5, vcc, 0, v3, vcc
	global_load_dword v23, v[4:5], off nt
	v_add_co_u32_e32 v4, vcc, s9, v2
	s_mov_b32 s9, 0x14000
	s_nop 0
	v_addc_co_u32_e32 v5, vcc, 0, v3, vcc
	global_load_dword v24, v[4:5], off nt
	v_add_co_u32_e32 v4, vcc, s9, v2
	s_mov_b32 s9, 0x18000
	s_nop 0
	v_addc_co_u32_e32 v5, vcc, 0, v3, vcc
	global_load_dword v25, v[4:5], off nt
	v_add_co_u32_e32 v4, vcc, s23, v2
	s_nop 1
	v_addc_co_u32_e32 v5, vcc, 0, v3, vcc
	global_load_dword v26, v[4:5], off nt
	v_add_co_u32_e32 v4, vcc, s9, v2
	s_mov_b32 s9, 0x1a000
	s_nop 0
	v_addc_co_u32_e32 v5, vcc, 0, v3, vcc
	global_load_dword v27, v[4:5], off nt
	v_add_co_u32_e32 v4, vcc, s9, v2
	s_mov_b32 s9, 0x1c000
	s_nop 0
	v_addc_co_u32_e32 v5, vcc, 0, v3, vcc
	global_load_dword v28, v[4:5], off nt
	v_add_co_u32_e32 v4, vcc, s9, v2
	s_mov_b32 s9, 0x1e000
	s_nop 0
	v_addc_co_u32_e32 v5, vcc, 0, v3, vcc
	global_load_dword v29, v[4:5], off nt
	v_add_co_u32_e32 v4, vcc, s9, v2
	s_mov_b32 s9, 0x20000
	s_nop 0
	v_addc_co_u32_e32 v5, vcc, 0, v3, vcc
	global_load_dword v30, v[4:5], off nt
	v_add_co_u32_e32 v4, vcc, s9, v2
	s_mov_b32 s9, 0x22000
	s_nop 0
	v_addc_co_u32_e32 v5, vcc, 0, v3, vcc
	global_load_dword v31, v[4:5], off nt
	v_add_co_u32_e32 v4, vcc, s9, v2
	s_mov_b32 s9, 0x24000
	s_nop 0
	v_addc_co_u32_e32 v5, vcc, 0, v3, vcc
	global_load_dword v32, v[4:5], off nt
	v_add_co_u32_e32 v4, vcc, s9, v2
	s_mov_b32 s9, 0x28000
	s_nop 0
	v_addc_co_u32_e32 v5, vcc, 0, v3, vcc
	global_load_dword v33, v[4:5], off nt
	v_add_co_u32_e32 v4, vcc, s50, v2
	s_nop 1
	v_addc_co_u32_e32 v5, vcc, 0, v3, vcc
	global_load_dword v34, v[4:5], off nt
	v_add_co_u32_e32 v4, vcc, s9, v2
	s_mov_b32 s9, 0x2a000
	s_nop 0
	v_addc_co_u32_e32 v5, vcc, 0, v3, vcc
	global_load_dword v35, v[4:5], off nt
	v_add_co_u32_e32 v4, vcc, s9, v2
	s_mov_b32 s9, 0x2e000
	s_nop 0
	v_addc_co_u32_e32 v5, vcc, 0, v3, vcc
	global_load_dword v36, v[4:5], off nt
	v_add_co_u32_e32 v4, vcc, s51, v2
	s_nop 1
	v_addc_co_u32_e32 v5, vcc, 0, v3, vcc
	global_load_dword v37, v[4:5], off nt
	v_add_co_u32_e32 v4, vcc, s9, v2
	s_mov_b32 s9, 0x30000
	s_nop 0
	v_addc_co_u32_e32 v5, vcc, 0, v3, vcc
	global_load_dword v38, v[4:5], off nt
	v_add_co_u32_e32 v4, vcc, s9, v2
	s_mov_b32 s9, 0x32000
	s_nop 0
	v_addc_co_u32_e32 v5, vcc, 0, v3, vcc
	global_load_dword v39, v[4:5], off nt
	v_add_co_u32_e32 v4, vcc, s9, v2
	s_mov_b32 s9, 0x34000
	s_nop 0
	v_addc_co_u32_e32 v5, vcc, 0, v3, vcc
	global_load_dword v40, v[4:5], off nt
	v_add_co_u32_e32 v4, vcc, s9, v2
	s_mov_b32 s9, 0x36000
	s_nop 0
	v_addc_co_u32_e32 v5, vcc, 0, v3, vcc
	global_load_dword v41, v[4:5], off nt
	v_add_co_u32_e32 v4, vcc, s9, v2
	s_mov_b32 s9, 0x38000
	s_nop 0
	v_addc_co_u32_e32 v5, vcc, 0, v3, vcc
	global_load_dword v42, v[4:5], off nt
	v_add_co_u32_e32 v4, vcc, s9, v2
	s_mov_b32 s9, 0x3a000
	s_nop 0
	v_addc_co_u32_e32 v5, vcc, 0, v3, vcc
	global_load_dword v43, v[4:5], off nt
	v_add_co_u32_e32 v4, vcc, s9, v2
	s_mov_b32 s9, 0x3e000
	s_nop 0
	v_addc_co_u32_e32 v5, vcc, 0, v3, vcc
	global_load_dword v44, v[4:5], off nt
	v_add_co_u32_e32 v4, vcc, s52, v2
	s_nop 1
	v_addc_co_u32_e32 v5, vcc, 0, v3, vcc
	v_add_co_u32_e32 v2, vcc, s9, v2
	global_load_dword v4, v[4:5], off nt
	s_nop 0
	v_addc_co_u32_e32 v3, vcc, 0, v3, vcc
	global_load_dword v2, v[2:3], off nt
	s_waitcnt vmcnt(0)
; #define LAS __attribute__((address_space(3)))
; __device__ __forceinline__ unsigned pk2(float lo, float hi) { unsigned r; asm("v_cvt_pk_bf16_f32 %0, %1, %2" : "=v"(r) : "v"(lo), "v"(hi)); return r; }
; __device__ __forceinline__ void st16_wt(void* p, u32x4 v) { asm volatile("global_store_dwordx4 %0, %1, off sc1\n\ts_nop 1" :: "v"(p), "v"(v) : "memory"); }
; #define LDS_WAIT() asm volatile("s_waitcnt lgkmcnt(0)" ::: "memory")
;     ...
;     for (int i = 0; i < 32; ++i) scr[(2 * i + (lane >> 5)) * 33 + (lane & 31)] = v[i];
;     LDS_WAIT();
; #pragma unroll
;     for (int j = 0; j < 4; ++j) { const int n = (lane >> 3) + 8 * j; const LAS float* s = scr + (8 * c) * 33 + n;
;         u32x4 o; o.x = pk2(s[0 * 33] * g0.x, s[1 * 33] * g0.y); o.y = pk2(s[2 * 33] * g0.z, s[3 * 33] * g0.w); o.z = pk2(s[4 * 33] * g1.x, s[5 * 33] * g1.y); o.w = pk2(s[6 * 33] * g1.z, s[7 * 33] * g1.w);
;         const int nn = n0 + n; const int drow = (mode == 0) ? nn : (256 * (nn >> 7) + 128 * (mode - 1) + (nn & 127));
;         st16_wt(WT + (size_t)drow * K + (k0 ^ kshift) + 8 * c, o); }
;     LDS_WAIT();
	ds_write2_b32 v13, v0, v6 offset1:66
	ds_write2_b32 v13, v7, v8 offset0:132 offset1:198
	v_add_u32_e32 v0, 0x400, v13
	ds_write2_b32 v0, v9, v16 offset0:8 offset1:74
	ds_write2_b32 v0, v17, v22 offset0:140 offset1:206
	v_add_u32_e32 v0, 0x800, v13
	ds_write2_b32 v0, v23, v24 offset0:16 offset1:82
	ds_write2_b32 v0, v25, v26 offset0:148 offset1:214
	v_add_u32_e32 v0, 0xc00, v13
	ds_write2_b32 v0, v27, v28 offset0:24 offset1:90
	ds_write2_b32 v0, v29, v30 offset0:156 offset1:222
	v_add_u32_e32 v0, 0x1000, v13
	ds_write2_b32 v0, v31, v32 offset0:32 offset1:98
	ds_write2_b32 v0, v33, v34 offset0:164 offset1:230
	v_add_u32_e32 v0, 0x1400, v13
	s_mov_b32 s9, s63
	ds_write2_b32 v0, v35, v36 offset0:40 offset1:106
	ds_write2_b32 v0, v37, v38 offset0:172 offset1:238
	v_add_u32_e32 v0, 0x1800, v13
	s_lshl_b64 s[8:9], s[8:9], 1
	ds_write2_b32 v0, v39, v40 offset0:48 offset1:114
	ds_write2_b32 v0, v41, v42 offset0:180 offset1:246
	v_add_u32_e32 v0, 0x1c00, v13
	s_add_u32 s8, s29, s8
	ds_write2_b32 v0, v43, v44 offset0:56 offset1:122
	ds_write2_b32 v0, v4, v2 offset0:188 offset1:254
	s_addc_u32 s9, s28, s9
	v_lshlrev_b32_e32 v0, 1, v14
	s_waitcnt lgkmcnt(0)
	v_lshl_add_u64 v[2:3], s[8:9], 0, v[0:1]
	s_mov_b64 s[8:9], 0x2980000
	v_lshl_add_u64 v[6:7], v[2:3], 0, s[8:9]
	ds_read2_b32 v[2:3], v18 offset1:33
	ds_read2_b32 v[4:5], v18 offset0:66 offset1:99
	v_or_b32_e32 v0, s10, v15
	s_waitcnt lgkmcnt(1)
	v_cvt_pk_bf16_f32 v2, v2, v3
	s_waitcnt lgkmcnt(0)
	v_cvt_pk_bf16_f32 v3, v4, v5
	ds_read2_b32 v[4:5], v18 offset0:132 offset1:165
	ds_read2_b32 v[8:9], v18 offset0:198 offset1:231
	v_lshlrev_b32_e32 v0, 9, v0
	s_waitcnt lgkmcnt(1)
	v_cvt_pk_bf16_f32 v4, v4, v5
	s_waitcnt lgkmcnt(0)
	v_cvt_pk_bf16_f32 v5, v8, v9
	v_lshl_add_u64 v[8:9], v[6:7], 0, v[0:1]
	global_store_dwordx4 v[8:9], v[2:5], off sc1
	s_nop 1
	ds_read2_b32 v[2:3], v18 offset0:8 offset1:41
	ds_read2_b32 v[4:5], v18 offset0:74 offset1:107
	v_or_b32_e32 v0, s10, v19
	s_waitcnt lgkmcnt(1)
	v_cvt_pk_bf16_f32 v2, v2, v3
	s_waitcnt lgkmcnt(0)
	v_cvt_pk_bf16_f32 v3, v4, v5
	ds_read2_b32 v[4:5], v18 offset0:140 offset1:173
	ds_read2_b32 v[8:9], v18 offset0:206 offset1:239
	v_lshlrev_b32_e32 v0, 9, v0
	s_waitcnt lgkmcnt(1)
	v_cvt_pk_bf16_f32 v4, v4, v5
	s_waitcnt lgkmcnt(0)
	v_cvt_pk_bf16_f32 v5, v8, v9
	v_lshl_add_u64 v[8:9], v[6:7], 0, v[0:1]
	global_store_dwordx4 v[8:9], v[2:5], off sc1
	s_nop 1
	ds_read2_b32 v[2:3], v18 offset0:16 offset1:49
	ds_read2_b32 v[4:5], v18 offset0:82 offset1:115
	v_or_b32_e32 v0, s10, v20
	s_waitcnt lgkmcnt(1)
	v_cvt_pk_bf16_f32 v2, v2, v3
	s_waitcnt lgkmcnt(0)
	v_cvt_pk_bf16_f32 v3, v4, v5
	ds_read2_b32 v[4:5], v18 offset0:148 offset1:181
	ds_read2_b32 v[8:9], v18 offset0:214 offset1:247
	v_lshlrev_b32_e32 v0, 9, v0
	s_waitcnt lgkmcnt(1)
	v_cvt_pk_bf16_f32 v4, v4, v5
	s_waitcnt lgkmcnt(0)
	v_cvt_pk_bf16_f32 v5, v8, v9
	v_lshl_add_u64 v[8:9], v[6:7], 0, v[0:1]
	global_store_dwordx4 v[8:9], v[2:5], off sc1
	s_nop 1
	ds_read2_b32 v[2:3], v18 offset0:24 offset1:57
	ds_read2_b32 v[4:5], v18 offset0:90 offset1:123
	v_or_b32_e32 v0, s10, v21
	s_waitcnt lgkmcnt(1)
	v_cvt_pk_bf16_f32 v2, v2, v3
	s_waitcnt lgkmcnt(0)
	v_cvt_pk_bf16_f32 v3, v4, v5
	ds_read2_b32 v[4:5], v18 offset0:156 offset1:189
	v_lshlrev_b32_e32 v0, 9, v0
	s_waitcnt lgkmcnt(0)
	v_cvt_pk_bf16_f32 v4, v4, v5
	ds_read2_b32 v[8:9], v18 offset0:222 offset1:255
	s_waitcnt lgkmcnt(0)
	v_cvt_pk_bf16_f32 v5, v8, v9
	v_lshl_add_u64 v[6:7], v[6:7], 0, v[0:1]
	global_store_dwordx4 v[6:7], v[2:5], off sc1
	s_nop 1
	s_waitcnt lgkmcnt(0)
	s_mov_b64 s[8:9], 0

; #define LAS __attribute__((address_space(3)))
; __device__ __forceinline__ unsigned xb_ld(unsigned* p)              { return __hip_atomic_load(p, __ATOMIC_RELAXED, __HIP_MEMORY_SCOPE_AGENT); }
; __device__ __forceinline__ unsigned xb_add(unsigned* p, unsigned v) { return __hip_atomic_fetch_add(p, v, __ATOMIC_RELAXED, __HIP_MEMORY_SCOPE_AGENT); }
; __device__ __forceinline__ unsigned xb_xcc_id() { return (unsigned)__builtin_amdgcn_s_getreg((3 << 11) | 20) & 0xFu; }
; __device__ __forceinline__ void xcd_barrier_complete(unsigned* bar, unsigned x, unsigned& nloc, unsigned& nx) {
;     const unsigned G = gridDim.x * gridDim.y * gridDim.z;
;     unsigned sum, cnt, mine, sp = 0u;
;     for (;;) {
;         sum = 0u; cnt = 0u; mine = 0u;
; #pragma unroll
;         for (unsigned j = 0; j < 16; ++j) { const unsigned c = xb_ld(&bar[XB_XCNT(j)]); sum += c; cnt += (c > 0u) ? 1u : 0u; mine = (j == x) ? c : mine; }
;         if (sum == G) break;
; __device__ __forceinline__ void xcd_barrier(unsigned* bar, volatile LAS unsigned* st) {
;     asm volatile("s_waitcnt vmcnt(0)" ::: "memory");
;     __syncthreads();
;     if (threadIdx.x == 0) {
;         const unsigned x = xb_xcc_id();
;         __builtin_amdgcn_s_waitcnt(0);
;         unsigned nloc = st[0], nx = st[1];
;         if (nloc == 0u) { xcd_barrier_complete(bar, x, nloc, nx); st[0] = nloc; st[1] = nx; }
;         const unsigned old = xb_add(&bar[XB_XSUB(x)], 1u);
.LBB0_310:
	s_mov_b64 s[6:7], s[40:41]
	s_waitcnt vmcnt(0)
	s_waitcnt vmcnt(0) lgkmcnt(0)
	s_barrier
	s_and_saveexec_b64 s[0:1], s[4:5]
	s_xor_b64 s[0:1], exec, s[0:1]
	s_cbranch_execz .LBB0_363
	v_readlane_b32 s9, v254, 26
	s_mov_b64 s[6:7], s[100:101]
	s_getreg_b32 s8, hwreg(HW_REG_XCC_ID, 0, 4)
	v_mov_b32_e32 v0, s9
	s_waitcnt vmcnt(0) expcnt(0) lgkmcnt(0)
	ds_read_b32 v3, v0
	v_readlane_b32 s9, v254, 24
	s_and_b32 s20, s8, 15
	s_waitcnt lgkmcnt(0)
	v_cmp_ne_u32_e32 vcc, 0, v3
	v_mov_b32_e32 v0, s9
	ds_read_b32 v0, v0
	s_cbranch_vccnz .LBB0_326
	s_add_u32 s8, s6, 0x12b90200
	s_addc_u32 s9, s7, 0
	s_add_u32 s10, s6, 0x12b90400
	s_addc_u32 s11, s7, 0
	s_add_u32 s16, s6, 0x12b90500
	s_addc_u32 s17, s7, 0
	s_add_u32 s26, s6, 0x12b90600
	s_addc_u32 s27, s7, 0
	s_add_u32 s28, s6, 0x12b90700
	s_addc_u32 s29, s7, 0
	s_add_u32 s42, s6, 0x12b90800
	s_addc_u32 s43, s7, 0
	s_add_u32 s44, s6, 0x12b90900
	s_addc_u32 s45, s7, 0
	s_add_u32 s46, s6, 0x12b90a00
	s_addc_u32 s47, s7, 0
	s_add_u32 s54, s6, 0x12b90b00
	s_addc_u32 s55, s7, 0
	s_add_u32 s56, s6, 0x12b90c00
	s_addc_u32 s57, s7, 0
	s_add_u32 s58, s6, 0x12b90d00
	s_addc_u32 s59, s7, 0
	s_add_u32 s60, s6, 0x12b90e00
	s_addc_u32 s61, s7, 0
	s_add_u32 s70, s6, 0x12b90f00
	s_addc_u32 s71, s7, 0
	s_add_u32 s78, s6, 0x12b91000
	s_addc_u32 s79, s7, 0
	s_add_u32 s92, s6, 0x12b91100
	s_addc_u32 s93, s7, 0
	s_add_u32 s30, s6, 0x12b91200
	s_addc_u32 s31, s7, 0
	s_add_u32 s76, s6, 0x12b91300
	s_addc_u32 s77, s7, 0
	s_mov_b32 s24, 1
	s_branch .LBB0_314

; #define PG8_WAIT_V(n) asm volatile("s_waitcnt vmcnt(" #n ")" ::: "memory")
; #define PG8_BAR __builtin_amdgcn_s_barrier()
; template <class Epi, class Pre, bool AG = false>
; __device__ __forceinline__ void gemm_phase(LAS unsigned char* lds, const Gemm g, const StaticOrder& S, const Epi& E, const Pre& P) {
;     ...
;     const int tid = tid_, wid = __builtin_amdgcn_readfirstlane(tid >> 6), lane = tid & 63, wr = wid >> 2, wc = wid & 3, fr = lane & 15, fq = lane >> 4;
;     const int K = g.K, nt = K / BK;
;     unsigned voffA[2], voffB[2];
; #pragma unroll
;     for (int i = 0; i < 2; ++i) { int R, C; stage_rc(tid * 16 + i * 8192, R, C); const int Rb = Epi::PERM ? ((R & ~31) + perm32(R & 31)) : R;
;         voffA[i] = AG ? (unsigned)((C >> 4) * g.M * 16 + R * 16 + (C & 15)) * 2u : (unsigned)(R * K + C) * 2u; voffB[i] = (unsigned)(Rb * K + C) * 2u; }
;     const size_t kstep = (size_t)(BK * 2), kstepA = AG ? (size_t)(BK / 16) * g.M * 32 : kstep;
;     const size_t hstep = (size_t)HALF * K * 2, hstepA = AG ? (size_t)HALF * 32 : hstep;
;     const size_t tstep = 2 * hstep, tstepA = 2 * hstepA;
;     const unsigned ldsw = (unsigned)wid * 1024u;
;     const int aoff = lds_byte(wr * 64 + fr, fq * 8), boff = lds_byte(wc * 32 + fr, fq * 8);
;     ...
;     Unit cur, nxt; int ui = 0;
;     if (!S.next(0, cur)) return;
;     f32x4 acc[2][2][4][2];
; #pragma unroll
;     for (int a = 0; a < 2; ++a)
; #pragma unroll
;         for (int b = 0; b < 2; ++b)
; #pragma unroll
;             for (int m = 0; m < 4; ++m)
; #pragma unroll
;                 for (int n = 0; n < 2; ++n) acc[a][b][m][n] = (f32x4){0.f, 0.f, 0.f, 0.f};
;     bf16x8 At[4][2], B0[2][2], B1[2][2];
;     const char* cA = (const char*)g.A + (size_t)cur.pm * tstepA; const char* cB = (const char*)g.Bt + (size_t)cur.pn * tstep;
;     PG8_STAGE(PG8_SB(0, 0), cB, voffB); PG8_STAGE(PG8_SB(0, 1), cB + hstep, voffB); PG8_STAGE(PG8_SA(0, 0), cA, voffA); PG8_STAGE(PG8_SA(0, 1), cA + hstepA, voffA);
;     P(S);
;     if (wr == 1) PG8_BAR;
;     PG8_WAIT_V(2); PG8_BAR;
;     PG8_STAGE(PG8_SB(1, 0), cB + kstep, voffB); PG8_STAGE(PG8_SA(1, 0), cA + kstepA, voffA); PG8_STAGE(PG8_SB(1, 1), cB + hstep + kstep, voffB);
;     PG8_WAIT_V(6); PG8_BAR;
; __global__ void __launch_bounds__(NTHR, 2) fwd_megakernel(Args a_unused) {
;     ...
;                 KArgs ka = kargs(); unsigned char* ws = ka->ws; unsigned char* wl = ws + (size_t)l * WL_SIZE;
.LBB0_363:
	s_or_b64 exec, exec, s[0:1]
	v_readlane_b32 s8, v254, 6
	v_readlane_b32 s9, v254, 7
	s_mov_b64 s[0:1], s[40:41]
	v_mov_b32_e32 v10, v234
	s_waitcnt lgkmcnt(0)
	v_cndmask_b32_e64 v0, 0, 1, s[8:9]
	s_xor_b64 s[92:93], s[94:95], -1
	s_barrier
	v_cmp_ne_u32_e64 s[6:7], 1, v0
	s_andn2_b64 vcc, exec, s[8:9]
	v_readfirstlane_b32 s10, v10
	s_cbranch_vccnz .LBB0_403
	v_lshlrev_b32_e32 v0, 4, v10
	v_add_u32_e32 v2, 0x2000, v0
	v_ashrrev_i32_e32 v3, 31, v2
	v_lshrrev_b32_e32 v3, 22, v3
	v_add_u32_e32 v3, v2, v3
	s_mov_b64 s[8:9], s[100:101]
	v_ashrrev_i32_e32 v11, 10, v3
	v_mul_i32_i24_e32 v3, 0x400, v11
	v_sub_u32_e32 v2, v2, v3
	v_lshrrev_b32_e32 v3, 4, v2
	v_readlane_b32 s0, v254, 20
	v_bitop3_b32 v2, v3, v2, 32 bitop3:0x6c
	s_waitcnt lgkmcnt(0)
	s_add_u32 s11, s8, s0
	v_readlane_b32 s0, v254, 22
	v_ashrrev_i32_e32 v3, 31, v2
	s_addc_u32 s16, s9, s0
	v_lshrrev_b32_e32 v3, 26, v3
	s_add_u32 s12, s8, 0x12b94000
	v_add_u32_e32 v3, v2, v3
	v_lshlrev_b32_e32 v4, 3, v11
	s_addc_u32 s13, s9, 0
	v_ashrrev_i32_e32 v12, 6, v3
	v_and_b32_e32 v4, -16, v4
	s_and_b64 s[0:1], s[94:95], exec
	v_add_u32_e32 v4, v12, v4
	v_and_b32_e32 v5, 3, v12
	s_mov_b32 s1, 0xffffe0
	v_lshrrev_b32_e32 v6, 2, v4
	v_lshlrev_b32_e32 v7, 1, v4
	v_and_or_b32 v5, v4, s1, v5
	v_and_b32_e32 v6, 4, v6
	v_and_b32_e32 v7, 24, v7
	v_and_b32_e32 v3, 0xc0, v3
	s_mov_b32 s0, 0x2200000
	v_or3_b32 v5, v5, v6, v7
	v_sub_u32_e32 v2, v2, v3
	v_mov_b32_e32 v7, 1
	s_cselect_b32 s0, 0xb00000, s0
	v_lshlrev_b32_e32 v6, 5, v11
	v_ashrrev_i16_sdwa v2, v7, sext(v2) dst_sel:DWORD dst_unused:UNUSED_PAD src0_sel:DWORD src1_sel:BYTE_0
	s_add_u32 s20, s11, s0
	v_and_b32_e32 v13, 32, v6
	v_bfe_i32 v14, v2, 0, 16
	s_movk_i32 s0, 0xb00
	v_mul_u32_u24_e32 v5, 0xb00, v5
	v_add_u32_e32 v2, v13, v14
	v_mul_lo_u32 v3, v4, s0
	v_add_lshl_u32 v154, v5, v2, 1
	v_add_lshl_u32 v156, v2, v3, 1
	v_bfe_i32 v2, v10, 27, 1
	v_lshrrev_b32_e32 v2, 22, v2
	v_add_u32_e32 v2, v0, v2
	v_and_b32_e32 v2, 0xfffffc00, v2
	v_sub_u32_e32 v0, v0, v2
	v_lshrrev_b32_e32 v2, 4, v0
	v_ashrrev_i32_e32 v3, 31, v10
	v_bitop3_b32 v0, v2, v0, 32 bitop3:0x6c
	v_lshrrev_b32_e32 v3, 26, v3
	v_ashrrev_i32_e32 v2, 31, v0
	v_add_u32_e32 v3, v10, v3
	v_lshrrev_b32_e32 v2, 26, v2
	v_ashrrev_i32_e32 v16, 6, v3
	v_add_u32_e32 v2, v0, v2
	v_lshlrev_b32_e32 v3, 3, v16
	v_ashrrev_i32_e32 v15, 6, v2
	v_and_b32_e32 v3, -16, v3
	v_add_u32_e32 v3, v15, v3
	v_and_b32_e32 v4, 3, v15
	v_lshrrev_b32_e32 v5, 2, v3
	v_lshlrev_b32_e32 v6, 1, v3
	v_and_b32_e32 v2, 0xc0, v2
	s_addc_u32 s24, s16, 0
	s_ashr_i32 s42, s10, 6
	v_and_or_b32 v4, v3, s1, v4
	v_and_b32_e32 v5, 4, v5
	v_and_b32_e32 v6, 24, v6
	v_sub_u32_e32 v0, v0, v2
	v_readlane_b32 s1, v254, 10
	s_ashr_i32 s11, s10, 8
	s_lshl_b32 s25, s42, 10
	v_or3_b32 v4, v4, v5, v6
	v_lshlrev_b32_e32 v5, 5, v16
	v_ashrrev_i16_sdwa v0, v7, sext(v0) dst_sel:DWORD dst_unused:UNUSED_PAD src0_sel:DWORD src1_sel:BYTE_0
	v_mul_lo_u32 v3, v3, s0
	s_mul_i32 s0, s1, 0x160000
	v_and_b32_e32 v17, 32, v5
	v_bfe_i32 v18, v0, 0, 16
	s_add_u32 s56, s20, s0
	s_mul_hi_i32 s0, s1, 0x160000
	v_mul_u32_u24_e32 v4, 0xb00, v4
	v_add_u32_e32 v2, v17, v18
	s_addc_u32 s57, s24, s0
	s_add_i32 s30, s25, 0
	v_add_lshl_u32 v0, v4, v2, 1
	s_add_i32 m0, s30, 0x10000
	v_add_lshl_u32 v158, v2, v3, 1
	global_load_lds_dwordx4 v0, s[56:57]
	s_add_i32 m0, s30, 0x12000
	s_add_u32 s0, s56, 0xb0000
	global_load_lds_dwordx4 v154, s[56:57]
	s_addc_u32 s1, s57, 0
	s_add_i32 m0, s30, 0x14000
	v_mov_b32_e32 v155, v1
	global_load_lds_dwordx4 v0, s[0:1]
	s_add_i32 m0, s30, 0x16000
	v_mov_b32_e32 v159, v1
	global_load_lds_dwordx4 v154, s[0:1]
	v_readlane_b32 s0, v254, 8
	s_mov_b32 s14, s0
	s_mul_i32 s0, s0, 0x160000
	s_add_u32 s54, s12, s0
	s_mul_hi_i32 s0, s14, 0x160000
	s_addc_u32 s55, s13, s0
	s_add_i32 s31, s30, 0x2000
	v_readlane_b32 s1, v254, 9
	s_mov_b32 m0, s30
	s_add_u32 s0, s54, 0xb0000
	global_load_lds_dwordx4 v158, s[54:55]
	s_mov_b32 m0, s31
	s_addc_u32 s1, s55, 0
	s_add_i32 s38, s30, 0x4000
	global_load_lds_dwordx4 v156, s[54:55]
	s_mov_b32 m0, s38
	s_add_i32 s48, s30, 0x6000
	global_load_lds_dwordx4 v158, s[0:1]
	s_mov_b32 m0, s48
	v_mov_b32_e32 v157, v1
	global_load_lds_dwordx4 v156, s[0:1]
	s_cmp_eq_u32 s11, 1
	v_lshl_add_u64 v[8:9], s[56:57], 0, v[0:1]
	v_lshl_add_u64 v[6:7], s[56:57], 0, v[154:155]
	v_lshl_add_u64 v[2:3], s[54:55], 0, v[158:159]
	s_cselect_b64 s[0:1], -1, 0
	s_cmp_lg_u32 s11, 1
	v_lshl_add_u64 v[4:5], s[54:55], 0, v[156:157]
	s_cbranch_scc1 .LBB0_366
	s_barrier

; #define LAS __attribute__((address_space(3)))
; __device__ __forceinline__ unsigned xb_ld(unsigned* p)              { return __hip_atomic_load(p, __ATOMIC_RELAXED, __HIP_MEMORY_SCOPE_AGENT); }
; __device__ __forceinline__ unsigned xb_add(unsigned* p, unsigned v) { return __hip_atomic_fetch_add(p, v, __ATOMIC_RELAXED, __HIP_MEMORY_SCOPE_AGENT); }
; __device__ __forceinline__ unsigned xb_xcc_id() { return (unsigned)__builtin_amdgcn_s_getreg((3 << 11) | 20) & 0xFu; }
; __device__ __forceinline__ void xcd_barrier_complete(unsigned* bar, unsigned x, unsigned& nloc, unsigned& nx) {
;     const unsigned G = gridDim.x * gridDim.y * gridDim.z;
;     unsigned sum, cnt, mine, sp = 0u;
;     for (;;) {
;         sum = 0u; cnt = 0u; mine = 0u;
; #pragma unroll
;         for (unsigned j = 0; j < 16; ++j) { const unsigned c = xb_ld(&bar[XB_XCNT(j)]); sum += c; cnt += (c > 0u) ? 1u : 0u; mine = (j == x) ? c : mine; }
;         if (sum == G) break;
; __device__ __forceinline__ void xcd_barrier(unsigned* bar, volatile LAS unsigned* st) {
;     asm volatile("s_waitcnt vmcnt(0)" ::: "memory");
;     __syncthreads();
;     if (threadIdx.x == 0) {
;         const unsigned x = xb_xcc_id();
;         __builtin_amdgcn_s_waitcnt(0);
;         unsigned nloc = st[0], nx = st[1];
;         if (nloc == 0u) { xcd_barrier_complete(bar, x, nloc, nx); st[0] = nloc; st[1] = nx; }
;         const unsigned old = xb_add(&bar[XB_XSUB(x)], 1u);
.LBB0_403:
	s_mov_b64 s[8:9], s[40:41]
	s_waitcnt vmcnt(0)
	s_waitcnt lgkmcnt(0)
	s_barrier
	s_and_saveexec_b64 s[0:1], s[4:5]
	s_cbranch_execz .LBB0_455
	v_readlane_b32 s11, v254, 26
	s_mov_b64 s[8:9], s[100:101]
	s_getreg_b32 s10, hwreg(HW_REG_XCC_ID, 0, 4)
	v_mov_b32_e32 v0, s11
	s_waitcnt vmcnt(0) expcnt(0) lgkmcnt(0)
	ds_read_b32 v3, v0
	v_readlane_b32 s11, v254, 24
	s_and_b32 s20, s10, 15
	s_waitcnt lgkmcnt(0)
	v_cmp_ne_u32_e32 vcc, 0, v3
	v_mov_b32_e32 v0, s11
	ds_read_b32 v2, v0
	s_cbranch_vccnz .LBB0_419
	s_add_u32 s10, s8, 0x12b90200
	s_addc_u32 s11, s9, 0
	s_add_u32 s16, s8, 0x12b90400
	s_addc_u32 s17, s9, 0
	s_add_u32 s26, s8, 0x12b90500
	s_addc_u32 s27, s9, 0
	s_add_u32 s28, s8, 0x12b90600
	s_addc_u32 s29, s9, 0
	s_add_u32 s42, s8, 0x12b90700
	s_addc_u32 s43, s9, 0
	s_add_u32 s44, s8, 0x12b90800
	s_addc_u32 s45, s9, 0
	s_add_u32 s46, s8, 0x12b90900
	s_addc_u32 s47, s9, 0
	s_add_u32 s54, s8, 0x12b90a00
	s_addc_u32 s55, s9, 0
	s_add_u32 s56, s8, 0x12b90b00
	s_addc_u32 s57, s9, 0
	s_add_u32 s58, s8, 0x12b90c00
	s_addc_u32 s59, s9, 0
	s_add_u32 s60, s8, 0x12b90d00
	s_addc_u32 s61, s9, 0
	s_add_u32 s70, s8, 0x12b90e00
	s_addc_u32 s71, s9, 0
	s_add_u32 s78, s8, 0x12b90f00
	s_addc_u32 s79, s9, 0
	s_add_u32 s94, s8, 0x12b91000
	s_addc_u32 s95, s9, 0
	s_add_u32 s30, s8, 0x12b91100
	s_addc_u32 s31, s9, 0
	s_add_u32 s76, s8, 0x12b91200
	s_addc_u32 s77, s9, 0
	s_add_u32 s12, s8, 0x12b91300
	s_addc_u32 s13, s9, 0
	s_mov_b32 s24, 1
	s_branch .LBB0_407

; #define PG8_WAIT_V(n) asm volatile("s_waitcnt vmcnt(" #n ")" ::: "memory")
; template <class Epi, class Pre, bool AG = false>
; __device__ __forceinline__ void gemm_phase(LAS unsigned char* lds, const Gemm g, const StaticOrder& S, const Epi& E, const Pre& P) {
;     ...
;     const int tid = tid_, wid = __builtin_amdgcn_readfirstlane(tid >> 6), lane = tid & 63, wr = wid >> 2, wc = wid & 3, fr = lane & 15, fq = lane >> 4;
;     const int K = g.K, nt = K / BK;
;     unsigned voffA[2], voffB[2];
; #pragma unroll
;     for (int i = 0; i < 2; ++i) { int R, C; stage_rc(tid * 16 + i * 8192, R, C); const int Rb = Epi::PERM ? ((R & ~31) + perm32(R & 31)) : R;
;         voffA[i] = AG ? (unsigned)((C >> 4) * g.M * 16 + R * 16 + (C & 15)) * 2u : (unsigned)(R * K + C) * 2u; voffB[i] = (unsigned)(Rb * K + C) * 2u; }
;     const size_t kstep = (size_t)(BK * 2), kstepA = AG ? (size_t)(BK / 16) * g.M * 32 : kstep;
;     const size_t hstep = (size_t)HALF * K * 2, hstepA = AG ? (size_t)HALF * 32 : hstep;
;     const size_t tstep = 2 * hstep, tstepA = 2 * hstepA;
;     const unsigned ldsw = (unsigned)wid * 1024u;
;     const int aoff = lds_byte(wr * 64 + fr, fq * 8), boff = lds_byte(wc * 32 + fr, fq * 8);
;     ...
;     Unit cur, nxt; int ui = 0;
;     if (!S.next(0, cur)) return;
;     f32x4 acc[2][2][4][2];
; #pragma unroll
;     for (int a = 0; a < 2; ++a)
; #pragma unroll
;         for (int b = 0; b < 2; ++b)
; #pragma unroll
;             for (int m = 0; m < 4; ++m)
; #pragma unroll
;                 for (int n = 0; n < 2; ++n) acc[a][b][m][n] = (f32x4){0.f, 0.f, 0.f, 0.f};
;     bf16x8 At[4][2], B0[2][2], B1[2][2];
;     const char* cA = (const char*)g.A + (size_t)cur.pm * tstepA; const char* cB = (const char*)g.Bt + (size_t)cur.pn * tstep;
;     PG8_STAGE(PG8_SB(0, 0), cB, voffB); PG8_STAGE(PG8_SB(0, 1), cB + hstep, voffB); PG8_STAGE(PG8_SA(0, 0), cA, voffA); PG8_STAGE(PG8_SA(0, 1), cA + hstepA, voffA);
;     P(S);
;     if (wr == 1) PG8_BAR;
;     PG8_WAIT_V(2); PG8_BAR;
;     PG8_STAGE(PG8_SB(1, 0), cB + kstep, voffB); PG8_STAGE(PG8_SA(1, 0), cA + kstepA, voffA); PG8_STAGE(PG8_SB(1, 1), cB + hstep + kstep, voffB);
;     PG8_WAIT_V(6); PG8_BAR;
; __global__ void __launch_bounds__(NTHR, 2) fwd_megakernel(Args a_unused) {
;     ...
;                 {
;                     KArgs ka = kargs(); unsigned char* ws = ka->ws; unsigned char* wl = ws + (size_t)l * WL_SIZE;
.LBB0_455:
	s_or_b64 exec, exec, s[0:1]
	s_mov_b64 s[0:1], -1
	s_and_b64 vcc, exec, s[92:93]
	s_waitcnt lgkmcnt(0)
	s_barrier
	s_cbranch_vccz .LBB0_555
	s_mov_b64 s[0:1], s[40:41]
	v_mov_b32_e32 v15, v234
	s_and_b64 vcc, exec, s[6:7]
	v_readfirstlane_b32 s44, v15
	s_cbranch_vccnz .LBB0_502
	v_lshlrev_b32_e32 v0, 4, v15
	v_add_u32_e32 v2, 0x2000, v0
	v_ashrrev_i32_e32 v3, 31, v2
	v_lshrrev_b32_e32 v3, 22, v3
	v_add_u32_e32 v3, v2, v3
	v_ashrrev_i32_e32 v10, 10, v3
	s_mov_b64 s[42:43], s[100:101]
	v_mul_i32_i24_e32 v3, 0x400, v10
	v_sub_u32_e32 v2, v2, v3
	v_lshrrev_b32_e32 v3, 4, v2
	v_bitop3_b32 v2, v3, v2, 32 bitop3:0x6c
	v_readlane_b32 s0, v254, 20
	v_ashrrev_i32_e32 v3, 31, v2
	s_waitcnt lgkmcnt(0)
	s_add_u32 s8, s42, s0
	v_readlane_b32 s0, v254, 22
	v_lshrrev_b32_e32 v3, 26, v3
	s_addc_u32 s9, s43, s0
	v_add_u32_e32 v3, v2, v3
	v_lshlrev_b32_e32 v4, 3, v10
	s_add_u32 s0, s42, 0xc910000
	v_ashrrev_i32_e32 v11, 6, v3
	v_and_b32_e32 v4, -16, v4
	s_addc_u32 s1, s43, 0
	v_add_u32_e32 v4, v11, v4
	s_add_u32 s30, s8, 0x2780000
	v_and_b32_e32 v5, 3, v11
	s_mov_b32 s8, 0x1fffe0
	v_lshrrev_b32_e32 v6, 2, v4
	v_lshlrev_b32_e32 v7, 1, v4
	v_and_b32_e32 v3, 0xc0, v3
	v_and_or_b32 v5, v4, s8, v5
	v_and_b32_e32 v6, 4, v6
	v_and_b32_e32 v7, 24, v7
	v_sub_u32_e32 v2, v2, v3
	v_mov_b32_e32 v8, 1
	v_or3_b32 v5, v5, v6, v7
	v_lshlrev_b32_e32 v6, 5, v10
	v_ashrrev_i16_sdwa v2, v8, sext(v2) dst_sel:DWORD dst_unused:UNUSED_PAD src0_sel:DWORD src1_sel:BYTE_0
	v_and_b32_e32 v6, 32, v6
	v_bfe_i32 v12, v2, 0, 16
	v_add_lshl_u32 v2, v6, v12, 1
	v_lshl_add_u32 v138, v5, 11, v2
	v_lshl_add_u32 v140, v4, 11, v2
	v_bfe_i32 v2, v15, 27, 1
	v_lshrrev_b32_e32 v2, 22, v2
	v_add_u32_e32 v2, v0, v2
	v_and_b32_e32 v2, 0xfffffc00, v2
	v_sub_u32_e32 v0, v0, v2
	v_lshrrev_b32_e32 v2, 4, v0
	v_ashrrev_i32_e32 v4, 31, v15
	v_bitop3_b32 v2, v2, v0, 32 bitop3:0x6c
	v_lshrrev_b32_e32 v4, 26, v4
	v_ashrrev_i32_e32 v0, 31, v2
	v_add_u32_e32 v4, v15, v4
	v_lshrrev_b32_e32 v0, 26, v0
	v_ashrrev_i32_e32 v13, 6, v4
	v_add_u32_e32 v3, v2, v0
	v_lshlrev_b32_e32 v4, 3, v13
	v_ashrrev_i32_e32 v0, 6, v3
	v_and_b32_e32 v4, -16, v4
	s_addc_u32 s31, s9, 0
	v_add_u32_e32 v4, v0, v4
	s_add_u32 s16, s42, 0x12a10000
	v_and_b32_e32 v5, 3, v0
	v_lshrrev_b32_e32 v6, 2, v4
	v_lshlrev_b32_e32 v7, 1, v4
	v_and_b32_e32 v3, 0xc0, v3
	s_addc_u32 s17, s43, 0
	s_ashr_i32 s20, s44, 6
	v_and_or_b32 v5, v4, s8, v5
	v_and_b32_e32 v6, 4, v6
	v_and_b32_e32 v7, 24, v7
	v_sub_u32_e32 v2, v2, v3
	s_lshl_b32 s48, s20, 10
	v_or3_b32 v5, v5, v6, v7
	v_lshlrev_b32_e32 v6, 5, v13
	v_ashrrev_i16_sdwa v2, v8, sext(v2) dst_sel:DWORD dst_unused:UNUSED_PAD src0_sel:DWORD src1_sel:BYTE_0
	v_readlane_b32 s8, v254, 58
	v_and_b32_e32 v6, 32, v6
	v_bfe_i32 v14, v2, 0, 16
	v_readlane_b32 s9, v254, 59
	s_add_u32 s54, s30, s8
	v_add_lshl_u32 v2, v6, v14, 1
	s_addc_u32 s55, s31, s9
	s_add_i32 s49, s48, 0
	v_lshl_add_u32 v142, v5, 11, v2
	s_add_i32 m0, s49, 0x10000
	v_lshl_add_u32 v144, v4, 11, v2
	global_load_lds_dwordx4 v142, s[54:55]
	s_add_i32 m0, s49, 0x12000
	s_add_u32 s8, s54, 0x40000
	global_load_lds_dwordx4 v138, s[54:55]
	s_addc_u32 s9, s55, 0
	s_add_i32 m0, s49, 0x14000
	v_mov_b32_e32 v143, v1
	global_load_lds_dwordx4 v142, s[8:9]
	s_add_i32 m0, s49, 0x16000
	v_mov_b32_e32 v139, v1
	global_load_lds_dwordx4 v138, s[8:9]
	v_readlane_b32 s8, v254, 56
	v_readlane_b32 s9, v254, 57
	s_add_u32 s10, s0, s8
	s_addc_u32 s11, s1, s9
	s_add_i32 s38, s49, 0x2000
	s_mov_b32 m0, s49
	s_add_u32 s8, s10, 0x40000
	global_load_lds_dwordx4 v144, s[10:11]
	s_mov_b32 m0, s38
	s_addc_u32 s9, s11, 0
	s_add_i32 s58, s49, 0x4000
	global_load_lds_dwordx4 v140, s[10:11]
	s_mov_b32 m0, s58
	s_add_i32 s59, s49, 0x6000
	global_load_lds_dwordx4 v144, s[8:9]
	s_mov_b32 m0, s59
	v_mov_b32_e32 v145, v1
	global_load_lds_dwordx4 v140, s[8:9]
	v_mov_b32_e32 v141, v1
	v_mov_b32_e32 v16, v234
	s_movk_i32 s8, 0x100
	v_readlane_b32 s12, v254, 12
	v_lshl_add_u64 v[8:9], s[54:55], 0, v[142:143]
	v_lshl_add_u64 v[6:7], s[54:55], 0, v[138:139]
	v_lshl_add_u64 v[4:5], s[10:11], 0, v[144:145]
	v_lshl_add_u64 v[2:3], s[10:11], 0, v[140:141]
	s_movk_i32 s24, 0xc400
	v_cmp_gt_i32_e64 s[8:9], s8, v16
	v_lshl_add_u32 v17, v16, 2, s12
	s_mov_b64 s[26:27], s[2:3]
	s_branch .LBB0_460

; #define PG8_WAIT_V(n) asm volatile("s_waitcnt vmcnt(" #n ")" ::: "memory")
; template <class Epi, class Pre, bool AG = false>
; __device__ __forceinline__ void gemm_phase(LAS unsigned char* lds, const Gemm g, const StaticOrder& S, const Epi& E, const Pre& P) {
;     ...
;     const int tid = tid_, wid = __builtin_amdgcn_readfirstlane(tid >> 6), lane = tid & 63, wr = wid >> 2, wc = wid & 3, fr = lane & 15, fq = lane >> 4;
;     const int K = g.K, nt = K / BK;
;     unsigned voffA[2], voffB[2];
; #pragma unroll
;     for (int i = 0; i < 2; ++i) { int R, C; stage_rc(tid * 16 + i * 8192, R, C); const int Rb = Epi::PERM ? ((R & ~31) + perm32(R & 31)) : R;
;         voffA[i] = AG ? (unsigned)((C >> 4) * g.M * 16 + R * 16 + (C & 15)) * 2u : (unsigned)(R * K + C) * 2u; voffB[i] = (unsigned)(Rb * K + C) * 2u; }
;     const size_t kstep = (size_t)(BK * 2), kstepA = AG ? (size_t)(BK / 16) * g.M * 32 : kstep;
;     const size_t hstep = (size_t)HALF * K * 2, hstepA = AG ? (size_t)HALF * 32 : hstep;
;     const size_t tstep = 2 * hstep, tstepA = 2 * hstepA;
;     const unsigned ldsw = (unsigned)wid * 1024u;
;     const int aoff = lds_byte(wr * 64 + fr, fq * 8), boff = lds_byte(wc * 32 + fr, fq * 8);
;     ...
;     Unit cur, nxt; int ui = 0;
;     if (!S.next(0, cur)) return;
;     f32x4 acc[2][2][4][2];
; #pragma unroll
;     for (int a = 0; a < 2; ++a)
; #pragma unroll
;         for (int b = 0; b < 2; ++b)
; #pragma unroll
;             for (int m = 0; m < 4; ++m)
; #pragma unroll
;                 for (int n = 0; n < 2; ++n) acc[a][b][m][n] = (f32x4){0.f, 0.f, 0.f, 0.f};
;     bf16x8 At[4][2], B0[2][2], B1[2][2];
;     const char* cA = (const char*)g.A + (size_t)cur.pm * tstepA; const char* cB = (const char*)g.Bt + (size_t)cur.pn * tstep;
;     PG8_STAGE(PG8_SB(0, 0), cB, voffB); PG8_STAGE(PG8_SB(0, 1), cB + hstep, voffB); PG8_STAGE(PG8_SA(0, 0), cA, voffA); PG8_STAGE(PG8_SA(0, 1), cA + hstepA, voffA);
;     P(S);
;     if (wr == 1) PG8_BAR;
;     PG8_WAIT_V(2); PG8_BAR;
;     PG8_STAGE(PG8_SB(1, 0), cB + kstep, voffB); PG8_STAGE(PG8_SA(1, 0), cA + kstepA, voffA); PG8_STAGE(PG8_SB(1, 1), cB + hstep + kstep, voffB);
;     PG8_WAIT_V(6); PG8_BAR;
; __global__ void __launch_bounds__(NTHR, 2) fwd_megakernel(Args a_unused) {
;     ...
;                 {
;                     KArgs ka = kargs(); unsigned char* ws = ka->ws; unsigned char* wl = ws + (size_t)l * WL_SIZE;
.LBB0_555:
	s_and_b64 vcc, exec, s[0:1]
	s_cbranch_vccz .LBB0_196
	v_readlane_b32 s8, v254, 33
	s_mov_b64 s[0:1], s[40:41]
	v_mov_b32_e32 v14, v234
	v_readlane_b32 s9, v254, 34
	s_andn2_b64 vcc, exec, s[8:9]
	v_readfirstlane_b32 s26, v14
	s_cbranch_vccnz .LBB0_586
	v_lshlrev_b32_e32 v0, 4, v14
	v_add_u32_e32 v2, 0x2000, v0
	v_ashrrev_i32_e32 v3, 31, v2
	v_lshrrev_b32_e32 v3, 22, v3
	v_add_u32_e32 v3, v2, v3
	v_ashrrev_i32_e32 v10, 10, v3
	v_mul_i32_i24_e32 v3, 0x400, v10
	v_sub_u32_e32 v2, v2, v3
	v_lshrrev_b32_e32 v3, 4, v2
	v_bitop3_b32 v2, v3, v2, 32 bitop3:0x6c
	v_ashrrev_i32_e32 v3, 31, v2
	v_lshrrev_b32_e32 v3, 26, v3
	v_add_u32_e32 v3, v2, v3
	v_lshlrev_b32_e32 v4, 3, v10
	v_ashrrev_i32_e32 v11, 6, v3
	v_and_b32_e32 v4, -16, v4
	v_add_u32_e32 v4, v11, v4
	v_and_b32_e32 v5, 3, v11
	s_mov_b32 s8, 0x1fffe0
	v_lshrrev_b32_e32 v6, 2, v4
	v_lshlrev_b32_e32 v7, 1, v4
	v_and_b32_e32 v3, 0xc0, v3
	v_and_or_b32 v5, v4, s8, v5
	v_and_b32_e32 v6, 4, v6
	v_and_b32_e32 v7, 24, v7
	v_sub_u32_e32 v2, v2, v3
	v_mov_b32_e32 v8, 1
	v_or3_b32 v5, v5, v6, v7
	v_lshlrev_b32_e32 v6, 5, v10
	v_ashrrev_i16_sdwa v2, v8, sext(v2) dst_sel:DWORD dst_unused:UNUSED_PAD src0_sel:DWORD src1_sel:BYTE_0
	v_and_b32_e32 v6, 32, v6
	v_bfe_i32 v12, v2, 0, 16
	v_add_lshl_u32 v2, v6, v12, 1
	v_lshl_add_u32 v130, v5, 11, v2
	v_lshl_add_u32 v132, v4, 11, v2
	v_bfe_i32 v2, v14, 27, 1
	s_mov_b64 s[10:11], s[100:101]
	v_lshrrev_b32_e32 v2, 22, v2
	v_add_u32_e32 v2, v0, v2
	v_and_b32_e32 v2, 0xfffffc00, v2
	v_sub_u32_e32 v0, v0, v2
	v_readlane_b32 s0, v254, 20
	v_lshrrev_b32_e32 v2, 4, v0
	v_ashrrev_i32_e32 v4, 31, v14
	s_waitcnt lgkmcnt(0)
	s_add_u32 s0, s10, s0
	v_readlane_b32 s1, v254, 22
	v_bitop3_b32 v2, v2, v0, 32 bitop3:0x6c
	v_lshrrev_b32_e32 v4, 26, v4
	s_addc_u32 s1, s11, s1
	v_ashrrev_i32_e32 v0, 31, v2
	v_add_u32_e32 v4, v14, v4
	s_add_u32 s20, s10, 0xc910000
	v_lshrrev_b32_e32 v0, 26, v0
	v_ashrrev_i32_e32 v13, 6, v4
	s_addc_u32 s24, s11, 0
	v_add_u32_e32 v3, v2, v0
	v_lshlrev_b32_e32 v4, 3, v13
	s_add_u32 s25, s0, 0x1080000
	v_ashrrev_i32_e32 v0, 6, v3
	v_and_b32_e32 v4, -16, v4
	s_addc_u32 s30, s1, 0
	v_add_u32_e32 v4, v0, v4
	s_add_u32 s0, s10, 0x12a10000
	v_and_b32_e32 v5, 3, v0
	v_lshrrev_b32_e32 v6, 2, v4
	v_lshlrev_b32_e32 v7, 1, v4
	v_and_b32_e32 v3, 0xc0, v3
	s_addc_u32 s1, s11, 0
	s_ashr_i32 s27, s26, 6
	v_and_or_b32 v5, v4, s8, v5
	v_and_b32_e32 v6, 4, v6
	v_and_b32_e32 v7, 24, v7
	v_sub_u32_e32 v2, v2, v3
	s_lshl_b32 s31, s27, 10
	v_or3_b32 v5, v5, v6, v7
	v_lshlrev_b32_e32 v6, 5, v13
	v_ashrrev_i16_sdwa v2, v8, sext(v2) dst_sel:DWORD dst_unused:UNUSED_PAD src0_sel:DWORD src1_sel:BYTE_0
	v_readlane_b32 s8, v254, 51
	v_and_b32_e32 v6, 32, v6
	v_bfe_i32 v15, v2, 0, 16
	v_readlane_b32 s9, v254, 52
	s_add_u32 s54, s25, s8
	v_add_lshl_u32 v2, v6, v15, 1
	s_addc_u32 s55, s30, s9
	s_add_i32 s38, s31, 0
	v_lshl_add_u32 v134, v5, 11, v2
	s_add_i32 m0, s38, 0x10000
	v_lshl_add_u32 v136, v4, 11, v2
	global_load_lds_dwordx4 v134, s[54:55]
	s_add_i32 m0, s38, 0x12000
	s_add_u32 s8, s54, 0x40000
	global_load_lds_dwordx4 v130, s[54:55]
	s_addc_u32 s9, s55, 0
	s_add_i32 m0, s38, 0x14000
	v_mov_b32_e32 v135, v1
	global_load_lds_dwordx4 v134, s[8:9]
	s_add_i32 m0, s38, 0x16000
	v_mov_b32_e32 v131, v1
	global_load_lds_dwordx4 v130, s[8:9]
	v_readlane_b32 s8, v254, 49
	v_readlane_b32 s9, v254, 50
	s_add_u32 s46, s20, s8
	s_addc_u32 s47, s24, s9
	s_add_i32 s48, s38, 0x2000
	s_mov_b32 m0, s38
	s_add_u32 s8, s46, 0x40000
	global_load_lds_dwordx4 v136, s[46:47]
	s_mov_b32 m0, s48
	s_addc_u32 s9, s47, 0
	s_add_i32 s49, s38, 0x4000
	global_load_lds_dwordx4 v132, s[46:47]
	s_mov_b32 m0, s49
	s_add_i32 s53, s38, 0x6000
	global_load_lds_dwordx4 v136, s[8:9]
	s_mov_b32 m0, s53
	v_mov_b32_e32 v137, v1
	global_load_lds_dwordx4 v132, s[8:9]
	v_mov_b32_e32 v133, v1
	v_mov_b32_e32 v16, v234
	s_movk_i32 s8, 0x100
	v_readlane_b32 s12, v254, 12
	v_lshl_add_u64 v[8:9], s[54:55], 0, v[134:135]
	v_lshl_add_u64 v[6:7], s[54:55], 0, v[130:131]
	v_lshl_add_u64 v[4:5], s[46:47], 0, v[136:137]
	v_lshl_add_u64 v[2:3], s[46:47], 0, v[132:133]
	s_movk_i32 s28, 0xc400
	v_cmp_gt_i32_e64 s[8:9], s8, v16
	v_lshl_add_u32 v17, v16, 2, s12
	s_mov_b64 s[16:17], s[2:3]
	s_cmp_eq_u32 s18, 0x100
	s_cbranch_scc1 .Lpr_win_begin
	s_branch .LBB0_560

; #define LAS __attribute__((address_space(3)))
; __device__ __forceinline__ unsigned xb_ld(unsigned* p)              { return __hip_atomic_load(p, __ATOMIC_RELAXED, __HIP_MEMORY_SCOPE_AGENT); }
; __device__ __forceinline__ unsigned xb_add(unsigned* p, unsigned v) { return __hip_atomic_fetch_add(p, v, __ATOMIC_RELAXED, __HIP_MEMORY_SCOPE_AGENT); }
; __device__ __forceinline__ unsigned xb_xcc_id() { return (unsigned)__builtin_amdgcn_s_getreg((3 << 11) | 20) & 0xFu; }
; __device__ __forceinline__ void xcd_barrier_complete(unsigned* bar, unsigned x, unsigned& nloc, unsigned& nx) {
;     const unsigned G = gridDim.x * gridDim.y * gridDim.z;
;     unsigned sum, cnt, mine, sp = 0u;
;     for (;;) {
;         sum = 0u; cnt = 0u; mine = 0u;
; #pragma unroll
;         for (unsigned j = 0; j < 16; ++j) { const unsigned c = xb_ld(&bar[XB_XCNT(j)]); sum += c; cnt += (c > 0u) ? 1u : 0u; mine = (j == x) ? c : mine; }
;         if (sum == G) break;
; __device__ __forceinline__ void xcd_barrier(unsigned* bar, volatile LAS unsigned* st) {
;     asm volatile("s_waitcnt vmcnt(0)" ::: "memory");
;     __syncthreads();
;     if (threadIdx.x == 0) {
;         const unsigned x = xb_xcc_id();
;         __builtin_amdgcn_s_waitcnt(0);
;         unsigned nloc = st[0], nx = st[1];
;         if (nloc == 0u) { xcd_barrier_complete(bar, x, nloc, nx); st[0] = nloc; st[1] = nx; }
;         const unsigned old = xb_add(&bar[XB_XSUB(x)], 1u);
.LBB0_586:
	s_mov_b64 s[8:9], s[40:41]
	s_waitcnt vmcnt(0)
	s_waitcnt vmcnt(0)
	s_barrier
	s_and_saveexec_b64 s[0:1], s[4:5]
	s_cbranch_execz .LBB0_638
	v_readlane_b32 s11, v254, 26
	s_mov_b64 s[8:9], s[100:101]
	s_getreg_b32 s10, hwreg(HW_REG_XCC_ID, 0, 4)
	v_mov_b32_e32 v0, s11
	s_waitcnt vmcnt(0) expcnt(0) lgkmcnt(0)
	ds_read_b32 v3, v0
	v_readlane_b32 s11, v254, 24
	s_and_b32 s20, s10, 15
	s_waitcnt lgkmcnt(0)
	v_cmp_ne_u32_e32 vcc, 0, v3
	v_mov_b32_e32 v0, s11
	ds_read_b32 v2, v0
	s_cbranch_vccnz .LBB0_602
	s_add_u32 s10, s8, 0x12b90200
	s_addc_u32 s11, s9, 0
	s_add_u32 s16, s8, 0x12b90400
	s_addc_u32 s17, s9, 0
	s_add_u32 s26, s8, 0x12b90500
	s_addc_u32 s27, s9, 0
	s_add_u32 s28, s8, 0x12b90600
	s_addc_u32 s29, s9, 0
	s_add_u32 s42, s8, 0x12b90700
	s_addc_u32 s43, s9, 0
	s_add_u32 s44, s8, 0x12b90800
	s_addc_u32 s45, s9, 0
	s_add_u32 s46, s8, 0x12b90900
	s_addc_u32 s47, s9, 0
	s_add_u32 s54, s8, 0x12b90a00
	s_addc_u32 s55, s9, 0
	s_add_u32 s56, s8, 0x12b90b00
	s_addc_u32 s57, s9, 0
	s_add_u32 s58, s8, 0x12b90c00
	s_addc_u32 s59, s9, 0
	s_add_u32 s60, s8, 0x12b90d00
	s_addc_u32 s61, s9, 0
	s_add_u32 s70, s8, 0x12b90e00
	s_addc_u32 s71, s9, 0
	s_add_u32 s78, s8, 0x12b90f00
	s_addc_u32 s79, s9, 0
	s_add_u32 s94, s8, 0x12b91000
	s_addc_u32 s95, s9, 0
	s_add_u32 s30, s8, 0x12b91100
	s_addc_u32 s31, s9, 0
	s_add_u32 s76, s8, 0x12b91200
	s_addc_u32 s77, s9, 0
	s_add_u32 s12, s8, 0x12b91300
	s_addc_u32 s13, s9, 0
	s_mov_b32 s24, 1
	s_branch .LBB0_590

; #define LAS __attribute__((address_space(3)))
; __device__ __forceinline__ KArgs kargs() { KArgs p = (KArgs)__builtin_amdgcn_kernarg_segment_ptr(); asm volatile("" : "+s"(p)); return p; }
; __device__ __forceinline__ void mixer_phase(LAS unsigned char* lds, const u16* z, u16* zg, u16* ya, const float* lbp, const u16* bbt, const u16* cm, const float* Dp,
;                                             const float* cw, const float* cb, int bid, int tid_in) {
;     int tid = tid_in; asm volatile("" : "+v"(tid));
;     __syncthreads();
;     const int wave = __builtin_amdgcn_readfirstlane(tid >> 6), lane = tid & 63, fr = lane & 15, fq = lane >> 4;
; #pragma unroll 1
;     for (int rep5 = 0; rep5 < (EXP_S5 ? 2 : 1); ++rep5) {
;         if (rep5) __syncthreads();
;         const int b = bid >> 5, g = 4 * (bid & 7) + ((bid >> 3) & 3);
;         LAS unsigned* wl = (LAS unsigned*)(lds + wave * 8704);
;         LAS float* carry = (LAS float*)(lds + 8 * 8704);
;         const float lr = lbp[(g * 64 + lane) * 2], li = lbp[(g * 64 + lane) * 2 + 1];
;         const bf16x8 zero8 = {0, 0, 0, 0, 0, 0, 0, 0};
;         bf16x8 bfrag[8], cfrag[4];
; #pragma unroll
;         for (int nt = 0; nt < 8; ++nt) { bfrag[nt] = zero8; if (fq < 2) bfrag[nt] = *(const bf16x8*)(bbt + ((size_t)(g * 128 + 16 * nt + fr) * 16 + 8 * fq)); }
; #pragma unroll
;         for (int ks = 0; ks < 4; ++ks) cfrag[ks] = *(const bf16x8*)(cm + ((size_t)(g * 16 + fr) * 128 + 32 * ks + 8 * fq));
;         const f32x4 Dv = *(const f32x4*)(Dp + g * 16 + 4 * fq);
;         const size_t rowbase = (size_t)b * SEQ + wave * 256;
; __global__ void __launch_bounds__(NTHR, 2) fwd_megakernel(Args a_unused) {
;     ...
;                 {
;                     KArgs ka = kargs(); unsigned char* ws = ka->ws; unsigned char* wl = ws + (size_t)l * WL_SIZE;
;                     for (int rep = 0; rep < (EXP_MIX ? 2 : 1); ++rep)
;                     for (int task = bid; task < 256; task += G)
;                         mixer_phase(lds, WSP(u16, WS_Z), WSP(u16, WS_ZG), WSP(u16, WS_YC) + 512, (const float*)(wl + O_LB), (const u16*)(wl + O_BBT), (const u16*)(wl + O_CM), ka->in[I_SD] + (size_t)l * NGRP * NHC,
;                                     ka->in[I_CW] + (size_t)l * 3 * CW, ka->in[I_CB] + (size_t)l * CW, task, threadIdx.x);
.LBB0_638:
	s_or_b64 exec, exec, s[0:1]
	v_readlane_b32 s8, v254, 6
	v_readlane_b32 s9, v254, 7
	s_mov_b64 s[0:1], s[40:41]
	s_and_b64 vcc, exec, s[8:9]
	s_waitcnt lgkmcnt(0)
	s_barrier
	s_cbranch_vccz .LBB0_676
	s_mov_b64 s[12:13], s[100:101]
	s_load_dwordx2 s[16:17], s[0:1], 0x80
	s_load_dwordx4 s[24:27], s[0:1], 0x40
	v_readlane_b32 s0, v254, 20
	v_readlane_b32 s14, v255, 15
	s_waitcnt lgkmcnt(0)
	s_add_u32 s20, s12, s0
	v_readlane_b32 s0, v254, 22
	s_addc_u32 s28, s13, s0
	s_add_u32 s0, s12, 0x12b94000
	s_addc_u32 s1, s13, 0
	s_add_u32 s8, s12, 0x17b94400
	s_addc_u32 s9, s13, 0
	s_add_u32 s10, s20, 0x2a00000
	s_addc_u32 s11, s28, 0
	s_add_u32 s78, s20, 0x2a04000
	s_addc_u32 s79, s28, 0
	s_add_u32 s94, s20, 0x2a24000
	s_addc_u32 s95, s28, 0
	v_readlane_b32 s20, v254, 4
	v_readlane_b32 s21, v254, 5
	s_add_u32 s31, s16, s20
	s_addc_u32 s48, s17, s21
	s_add_u32 s46, s24, s14
	v_readlane_b32 s14, v255, 14
	s_addc_u32 s47, s25, s14
	s_add_u32 s70, s26, s20
	s_addc_u32 s71, s27, s21
	s_add_u32 s16, s12, 0x16b94000
	v_readlane_b32 s30, v255, 7
	s_addc_u32 s17, s13, 0
	s_mov_b32 s49, s2
	s_cmp_eq_u32 s98, 0
	s_cbranch_scc1 .Lmix_noperm
	s_and_b32 s49, s2, 7
	s_lshl_b32 s49, s49, 5
	s_bfe_u32 s99, s2, 0x20003
	s_lshl_b32 s99, s99, 3
	s_or_b32 s49, s49, s99
	s_lshr_b32 s99, s2, 5
	s_or_b32 s49, s49, s99
	s_lshl_b32 s30, s49, 2

; #define LAS __attribute__((address_space(3)))
; __device__ __forceinline__ unsigned xb_add(unsigned* p, unsigned v) { return __hip_atomic_fetch_add(p, v, __ATOMIC_RELAXED, __HIP_MEMORY_SCOPE_AGENT); }
; __device__ __forceinline__ unsigned xb_xcc_id() { return (unsigned)__builtin_amdgcn_s_getreg((3 << 11) | 20) & 0xFu; }
; __device__ __forceinline__ void xcd_barrier(unsigned* bar, volatile LAS unsigned* st) {
;     asm volatile("s_waitcnt vmcnt(0)" ::: "memory");
;     __syncthreads();
;     if (threadIdx.x == 0) {
;         const unsigned x = xb_xcc_id();
;         __builtin_amdgcn_s_waitcnt(0);
;         unsigned nloc = st[0], nx = st[1];
;         if (nloc == 0u) { xcd_barrier_complete(bar, x, nloc, nx); st[0] = nloc; st[1] = nx; }
;         const unsigned old = xb_add(&bar[XB_XSUB(x)], 1u);
.LBB0_676:
	s_mov_b64 s[8:9], s[40:41]
	s_waitcnt vmcnt(0)
	s_barrier
	s_and_saveexec_b64 s[0:1], s[4:5]
	s_cbranch_execz .LBB0_728
	v_readlane_b32 s11, v254, 26
	s_mov_b64 s[8:9], s[100:101]
	s_getreg_b32 s10, hwreg(HW_REG_XCC_ID, 0, 4)
	v_mov_b32_e32 v0, s11
	s_waitcnt vmcnt(0) expcnt(0) lgkmcnt(0)
	ds_read_b32 v3, v0
	v_readlane_b32 s11, v254, 24
	s_and_b32 s20, s10, 15
	s_waitcnt lgkmcnt(0)
	v_cmp_ne_u32_e32 vcc, 0, v3
	v_mov_b32_e32 v0, s11
	ds_read_b32 v2, v0
	s_cbranch_vccnz .LBB0_692
	s_add_u32 s10, s8, 0x12b90200
	s_addc_u32 s11, s9, 0
	s_add_u32 s16, s8, 0x12b90400
	s_addc_u32 s17, s9, 0
	s_add_u32 s26, s8, 0x12b90500
	s_addc_u32 s27, s9, 0
	s_add_u32 s28, s8, 0x12b90600
	s_addc_u32 s29, s9, 0
	s_add_u32 s42, s8, 0x12b90700
	s_addc_u32 s43, s9, 0
	s_add_u32 s44, s8, 0x12b90800
	s_addc_u32 s45, s9, 0
	s_add_u32 s46, s8, 0x12b90900
	s_addc_u32 s47, s9, 0
	s_add_u32 s54, s8, 0x12b90a00
	s_addc_u32 s55, s9, 0
	s_add_u32 s56, s8, 0x12b90b00
	s_addc_u32 s57, s9, 0
	s_add_u32 s58, s8, 0x12b90c00
	s_addc_u32 s59, s9, 0
	s_add_u32 s60, s8, 0x12b90d00
	s_addc_u32 s61, s9, 0
	s_add_u32 s70, s8, 0x12b90e00
	s_addc_u32 s71, s9, 0
	s_add_u32 s78, s8, 0x12b90f00
	s_addc_u32 s79, s9, 0
	s_add_u32 s94, s8, 0x12b91000
	s_addc_u32 s95, s9, 0
	s_add_u32 s30, s8, 0x12b91100
	s_addc_u32 s31, s9, 0
	s_add_u32 s76, s8, 0x12b91200
	s_addc_u32 s77, s9, 0
	s_add_u32 s12, s8, 0x12b91300
	s_addc_u32 s13, s9, 0
	s_mov_b32 s24, 1
	s_branch .LBB0_680

; #define PG8_WAIT_V(n) asm volatile("s_waitcnt vmcnt(" #n ")" ::: "memory")
; template <class Epi, class Pre, bool AG = false>
; __device__ __forceinline__ void gemm_phase(LAS unsigned char* lds, const Gemm g, const StaticOrder& S, const Epi& E, const Pre& P) {
;     ...
;     const int tid = tid_, wid = __builtin_amdgcn_readfirstlane(tid >> 6), lane = tid & 63, wr = wid >> 2, wc = wid & 3, fr = lane & 15, fq = lane >> 4;
;     const int K = g.K, nt = K / BK;
;     unsigned voffA[2], voffB[2];
; #pragma unroll
;     for (int i = 0; i < 2; ++i) { int R, C; stage_rc(tid * 16 + i * 8192, R, C); const int Rb = Epi::PERM ? ((R & ~31) + perm32(R & 31)) : R;
;         voffA[i] = AG ? (unsigned)((C >> 4) * g.M * 16 + R * 16 + (C & 15)) * 2u : (unsigned)(R * K + C) * 2u; voffB[i] = (unsigned)(Rb * K + C) * 2u; }
;     const size_t kstep = (size_t)(BK * 2), kstepA = AG ? (size_t)(BK / 16) * g.M * 32 : kstep;
;     const size_t hstep = (size_t)HALF * K * 2, hstepA = AG ? (size_t)HALF * 32 : hstep;
;     const size_t tstep = 2 * hstep, tstepA = 2 * hstepA;
;     const unsigned ldsw = (unsigned)wid * 1024u;
;     const int aoff = lds_byte(wr * 64 + fr, fq * 8), boff = lds_byte(wc * 32 + fr, fq * 8);
;     ...
;     Unit cur, nxt; int ui = 0;
;     if (!S.next(0, cur)) return;
;     f32x4 acc[2][2][4][2];
; #pragma unroll
;     for (int a = 0; a < 2; ++a)
; #pragma unroll
;         for (int b = 0; b < 2; ++b)
; #pragma unroll
;             for (int m = 0; m < 4; ++m)
; #pragma unroll
;                 for (int n = 0; n < 2; ++n) acc[a][b][m][n] = (f32x4){0.f, 0.f, 0.f, 0.f};
;     bf16x8 At[4][2], B0[2][2], B1[2][2];
;     const char* cA = (const char*)g.A + (size_t)cur.pm * tstepA; const char* cB = (const char*)g.Bt + (size_t)cur.pn * tstep;
;     PG8_STAGE(PG8_SB(0, 0), cB, voffB); PG8_STAGE(PG8_SB(0, 1), cB + hstep, voffB); PG8_STAGE(PG8_SA(0, 0), cA, voffA); PG8_STAGE(PG8_SA(0, 1), cA + hstepA, voffA);
;     P(S);
;     if (wr == 1) PG8_BAR;
;     PG8_WAIT_V(2); PG8_BAR;
;     PG8_STAGE(PG8_SB(1, 0), cB + kstep, voffB); PG8_STAGE(PG8_SA(1, 0), cA + kstepA, voffA); PG8_STAGE(PG8_SB(1, 1), cB + hstep + kstep, voffB);
;     PG8_WAIT_V(6); PG8_BAR;
; __global__ void __launch_bounds__(NTHR, 2) fwd_megakernel(Args a_unused) {
;     ...
;                 {
;                     KArgs ka = kargs(); unsigned char* ws = ka->ws; unsigned char* wl = ws + (size_t)l * WL_SIZE;
.LBB0_728:
	s_or_b64 exec, exec, s[0:1]
	v_readlane_b32 s8, v254, 35
	s_mov_b64 s[0:1], s[40:41]
	v_mov_b32_e32 v0, v234
	v_readlane_b32 s9, v254, 36
	s_waitcnt lgkmcnt(0)
	s_barrier
	s_andn2_b64 vcc, exec, s[8:9]
	v_readfirstlane_b32 s12, v0
	s_cbranch_vccnz .LBB0_764
	v_lshlrev_b32_e32 v2, 4, v0
	v_add_u32_e32 v3, 0x2000, v2
	v_ashrrev_i32_e32 v4, 31, v3
	v_lshrrev_b32_e32 v4, 22, v4
	v_add_u32_e32 v4, v3, v4
	v_ashrrev_i32_e32 v6, 10, v4
	v_mul_i32_i24_e32 v4, 0x400, v6
	s_mov_b64 s[8:9], s[100:101]
	s_load_dwordx2 s[26:27], s[0:1], 0x98
	v_sub_u32_e32 v3, v3, v4
	v_lshrrev_b32_e32 v4, 4, v3
	v_bitop3_b32 v3, v4, v3, 32 bitop3:0x6c
	v_readlane_b32 s0, v254, 20
	v_ashrrev_i32_e32 v4, 31, v3
	s_waitcnt lgkmcnt(0)
	s_add_u32 s10, s8, s0
	v_readlane_b32 s0, v254, 22
	v_lshrrev_b32_e32 v4, 26, v4
	s_addc_u32 s11, s9, s0
	v_add_u32_e32 v4, v3, v4
	v_lshlrev_b32_e32 v5, 3, v6
	s_add_u32 s0, s8, 0x16b94000
	v_ashrrev_i32_e32 v7, 6, v4
	v_and_b32_e32 v5, -16, v5
	s_addc_u32 s1, s9, 0
	v_add_u32_e32 v5, v7, v5
	s_add_u32 s30, s10, 0x1480000
	v_and_b32_e32 v8, 3, v7
	s_mov_b32 s10, 0x3fffe0
	v_lshrrev_b32_e32 v9, 2, v5
	v_lshlrev_b32_e32 v10, 1, v5
	v_and_or_b32 v8, v5, s10, v8
	v_and_b32_e32 v9, 4, v9
	v_and_b32_e32 v10, 24, v10
	v_and_b32_e32 v4, 0xc0, v4
	v_or3_b32 v8, v8, v9, v10
	v_lshlrev_b32_e32 v9, 5, v6
	v_sub_u32_e32 v3, v3, v4
	v_mov_b32_e32 v14, 1
	v_and_b32_e32 v9, 32, v9
	v_ashrrev_i16_sdwa v3, v14, sext(v3) dst_sel:DWORD dst_unused:UNUSED_PAD src0_sel:DWORD src1_sel:BYTE_0
	v_add_u32_sdwa v4, v9, sext(v3) dst_sel:DWORD dst_unused:UNUSED_PAD src0_sel:DWORD src1_sel:WORD_0
	v_lshlrev_b32_e32 v9, 1, v4
	v_lshlrev_b32_e32 v4, 14, v4
	v_lshl_add_u32 v194, v8, 10, v9
	v_and_b32_e32 v8, 0x7ffc0000, v4
	v_mov_b32_e32 v15, 15
	v_lshl_add_u32 v4, v5, 4, v8
	v_and_b32_sdwa v9, sext(v3), v15 dst_sel:DWORD dst_unused:UNUSED_PAD src0_sel:WORD_0 src1_sel:DWORD
	v_or_b32_e32 v3, v4, v9
	v_lshlrev_b32_e32 v196, 1, v3
	v_bfe_i32 v3, v0, 27, 1
	v_lshrrev_b32_e32 v3, 22, v3
	v_add_u32_e32 v3, v2, v3
	v_and_b32_e32 v3, 0xfffffc00, v3
	v_sub_u32_e32 v2, v2, v3
	v_lshrrev_b32_e32 v3, 4, v2
	v_ashrrev_i32_e32 v4, 31, v0
	v_bitop3_b32 v2, v3, v2, 32 bitop3:0x6c
	v_lshrrev_b32_e32 v4, 26, v4
	v_ashrrev_i32_e32 v3, 31, v2
	v_add_u32_e32 v4, v0, v4
	v_lshrrev_b32_e32 v3, 26, v3
	v_ashrrev_i32_e32 v11, 6, v4
	v_add_u32_e32 v3, v2, v3
	v_lshlrev_b32_e32 v4, 3, v11
	v_ashrrev_i32_e32 v10, 6, v3
	v_and_b32_e32 v4, -16, v4
	v_add_u32_e32 v4, v10, v4
	v_and_b32_e32 v5, 3, v10
	v_lshrrev_b32_e32 v12, 2, v4
	v_lshlrev_b32_e32 v13, 1, v4
	v_and_or_b32 v5, v4, s10, v5
	v_and_b32_e32 v12, 4, v12
	v_and_b32_e32 v13, 24, v13
	v_and_b32_e32 v3, 0xc0, v3
	s_addc_u32 s31, s11, 0
	s_ashr_i32 s20, s12, 6
	v_or3_b32 v5, v5, v12, v13
	v_lshlrev_b32_e32 v12, 5, v11
	v_sub_u32_e32 v2, v2, v3
	s_ashr_i32 s13, s12, 8
	s_lshl_b32 s48, s20, 10
	v_and_b32_e32 v12, 32, v12
	v_ashrrev_i16_sdwa v2, v14, sext(v2) dst_sel:DWORD dst_unused:UNUSED_PAD src0_sel:DWORD src1_sel:BYTE_0
	v_readlane_b32 s10, v255, 0
	v_add_u32_sdwa v3, v12, sext(v2) dst_sel:DWORD dst_unused:UNUSED_PAD src0_sel:DWORD src1_sel:WORD_0
	v_readlane_b32 s11, v255, 1
	s_add_u32 s54, s30, s10
	v_lshlrev_b32_e32 v12, 1, v3
	s_addc_u32 s55, s31, s11
	s_add_i32 s49, s48, 0
	v_lshl_add_u32 v198, v5, 10, v12
	s_add_i32 m0, s49, 0x10000
	v_lshlrev_b32_e32 v3, 14, v3
	global_load_lds_dwordx4 v198, s[54:55]
	s_add_i32 m0, s49, 0x12000
	s_add_u32 s10, s54, 0x20000
	global_load_lds_dwordx4 v194, s[54:55]
	s_addc_u32 s11, s55, 0
	s_add_i32 m0, s49, 0x14000
	v_and_b32_e32 v12, 0x7ffc0000, v3
	global_load_lds_dwordx4 v198, s[10:11]
	s_add_i32 m0, s49, 0x16000
	v_lshl_add_u32 v3, v4, 4, v12
	global_load_lds_dwordx4 v194, s[10:11]
	v_readlane_b32 s10, v254, 62
	v_and_b32_sdwa v13, sext(v2), v15 dst_sel:DWORD dst_unused:UNUSED_PAD src0_sel:WORD_0 src1_sel:DWORD
	v_readlane_b32 s11, v254, 63
	s_add_u32 s10, s0, s10
	v_or_b32_e32 v2, v3, v13
	s_addc_u32 s11, s1, s11
	s_add_i32 s76, s49, 0x2000
	v_lshlrev_b32_e32 v200, 1, v2
	s_mov_b32 m0, s49
	s_add_u32 s16, s10, 0x1000
	global_load_lds_dwordx4 v200, s[10:11]
	s_mov_b32 m0, s76
	s_addc_u32 s17, s11, 0
	s_add_i32 s77, s49, 0x4000
	global_load_lds_dwordx4 v196, s[10:11]
	s_mov_b32 m0, s77
	s_add_i32 s84, s49, 0x6000
	global_load_lds_dwordx4 v200, s[16:17]
	s_mov_b32 m0, s84
	v_mov_b32_e32 v199, v1
	global_load_lds_dwordx4 v196, s[16:17]
	v_mov_b32_e32 v195, v1
	s_cmp_eq_u32 s13, 1
	v_lshl_add_u64 v[2:3], s[54:55], 0, v[198:199]
	s_cselect_b64 s[16:17], -1, 0
	s_cmp_lg_u32 s13, 1
	v_lshl_add_u64 v[4:5], s[54:55], 0, v[194:195]
	s_cbranch_scc1 .LBB0_731
	s_barrier

; __device__ __forceinline__ KArgs kargs() { KArgs p = (KArgs)__builtin_amdgcn_kernarg_segment_ptr(); asm volatile("" : "+s"(p)); return p; }
; __global__ void __launch_bounds__(NTHR, 2) fwd_megakernel(Args a_unused) {
;     ...
;                 {
;                     KArgs ka = kargs(); unsigned char* ws = ka->ws; unsigned char* wl = ws + (size_t)l * WL_SIZE;
;                     pg8::Gemm g{WSP(u16, WS_PB) + (size_t)l * M * PLE, (const u16*)(wl + O_PP), M, D, PLE}; pg8::StaticOrder S;
;                     if (defer) S.init(M, D, bid >= 128 ? 128 : 1, bid >= 128 ? bid - 128 : 1 << 20); else S.init(M, D, G, (bid + G / 2) % G);
;                     EpiBf<false> E{WSP(u16, WS_PJ), D, lds};
;                     pg8::gemm_phase<EpiBf<false>, NoPrep>(lds, g, S, E, NoPrep{});
;                 }
.LBB0_764:
	s_mov_b64 s[0:1], s[40:41]
	s_mov_b64 s[8:9], s[100:101]
	v_readlane_b32 s0, v254, 2
	v_readlane_b32 s1, v254, 3
	s_and_b64 vcc, exec, s[0:1]
	v_readlane_b32 s20, v254, 37
	v_readlane_b32 s12, v254, 38
	s_cbranch_vccz .LBB0_766
	s_load_dwordx2 s[0:1], s[40:41], 0x108
	v_readlane_b32 s12, v255, 2
	s_waitcnt lgkmcnt(0)
	s_mov_b32 s20, s0

; #define LAS __attribute__((address_space(3)))
; __device__ __forceinline__ unsigned xb_add(unsigned* p, unsigned v) { return __hip_atomic_fetch_add(p, v, __ATOMIC_RELAXED, __HIP_MEMORY_SCOPE_AGENT); }
; __device__ __forceinline__ unsigned xb_xcc_id() { return (unsigned)__builtin_amdgcn_s_getreg((3 << 11) | 20) & 0xFu; }
; __device__ __forceinline__ void xcd_barrier(unsigned* bar, volatile LAS unsigned* st) {
;     asm volatile("s_waitcnt vmcnt(0)" ::: "memory");
;     __syncthreads();
;     if (threadIdx.x == 0) {
;         const unsigned x = xb_xcc_id();
;         __builtin_amdgcn_s_waitcnt(0);
;         unsigned nloc = st[0], nx = st[1];
;         if (nloc == 0u) { xcd_barrier_complete(bar, x, nloc, nx); st[0] = nloc; st[1] = nx; }
;         const unsigned old = xb_add(&bar[XB_XSUB(x)], 1u);
.LBB0_788:
	s_waitcnt lgkmcnt(0)
	s_mov_b64 s[8:9], s[40:41]
	s_waitcnt vmcnt(0)
	s_waitcnt vmcnt(0)
	s_barrier
	s_and_saveexec_b64 s[0:1], s[4:5]
	s_cbranch_execz .LBB0_840
	v_readlane_b32 s11, v254, 26
	s_mov_b64 s[8:9], s[100:101]
	s_getreg_b32 s10, hwreg(HW_REG_XCC_ID, 0, 4)
	v_mov_b32_e32 v0, s11
	s_waitcnt vmcnt(0) expcnt(0) lgkmcnt(0)
	ds_read_b32 v3, v0
	v_readlane_b32 s11, v254, 24
	s_and_b32 s20, s10, 15
	s_waitcnt lgkmcnt(0)
	v_cmp_ne_u32_e32 vcc, 0, v3
	v_mov_b32_e32 v0, s11
	ds_read_b32 v2, v0
	s_cbranch_vccnz .LBB0_804
	s_add_u32 s10, s8, 0x12b90200
	s_addc_u32 s11, s9, 0
	s_add_u32 s16, s8, 0x12b90400
	s_addc_u32 s17, s9, 0
	s_add_u32 s26, s8, 0x12b90500
	s_addc_u32 s27, s9, 0
	s_add_u32 s28, s8, 0x12b90600
	s_addc_u32 s29, s9, 0
	s_add_u32 s42, s8, 0x12b90700
	s_addc_u32 s43, s9, 0
	s_add_u32 s44, s8, 0x12b90800
	s_addc_u32 s45, s9, 0
	s_add_u32 s46, s8, 0x12b90900
	s_addc_u32 s47, s9, 0
	s_add_u32 s54, s8, 0x12b90a00
	s_addc_u32 s55, s9, 0
	s_add_u32 s56, s8, 0x12b90b00
	s_addc_u32 s57, s9, 0
	s_add_u32 s58, s8, 0x12b90c00
	s_addc_u32 s59, s9, 0
	s_add_u32 s60, s8, 0x12b90d00
	s_addc_u32 s61, s9, 0
	s_add_u32 s70, s8, 0x12b90e00
	s_addc_u32 s71, s9, 0
	s_add_u32 s78, s8, 0x12b90f00
	s_addc_u32 s79, s9, 0
	s_add_u32 s94, s8, 0x12b91000
	s_addc_u32 s95, s9, 0
	s_add_u32 s30, s8, 0x12b91100
	s_addc_u32 s31, s9, 0
	s_add_u32 s76, s8, 0x12b91200
	s_addc_u32 s77, s9, 0
	s_add_u32 s12, s8, 0x12b91300
	s_addc_u32 s13, s9, 0
	s_mov_b32 s24, 1
	s_branch .LBB0_792

; #define PG8_WAIT_V(n) asm volatile("s_waitcnt vmcnt(" #n ")" ::: "memory")
; template <class Epi, class Pre, bool AG = false>
; __device__ __forceinline__ void gemm_phase(LAS unsigned char* lds, const Gemm g, const StaticOrder& S, const Epi& E, const Pre& P) {
;     ...
;     const int tid = tid_, wid = __builtin_amdgcn_readfirstlane(tid >> 6), lane = tid & 63, wr = wid >> 2, wc = wid & 3, fr = lane & 15, fq = lane >> 4;
;     const int K = g.K, nt = K / BK;
;     unsigned voffA[2], voffB[2];
; #pragma unroll
;     for (int i = 0; i < 2; ++i) { int R, C; stage_rc(tid * 16 + i * 8192, R, C); const int Rb = Epi::PERM ? ((R & ~31) + perm32(R & 31)) : R;
;         voffA[i] = AG ? (unsigned)((C >> 4) * g.M * 16 + R * 16 + (C & 15)) * 2u : (unsigned)(R * K + C) * 2u; voffB[i] = (unsigned)(Rb * K + C) * 2u; }
;     const size_t kstep = (size_t)(BK * 2), kstepA = AG ? (size_t)(BK / 16) * g.M * 32 : kstep;
;     const size_t hstep = (size_t)HALF * K * 2, hstepA = AG ? (size_t)HALF * 32 : hstep;
;     const size_t tstep = 2 * hstep, tstepA = 2 * hstepA;
;     const unsigned ldsw = (unsigned)wid * 1024u;
;     const int aoff = lds_byte(wr * 64 + fr, fq * 8), boff = lds_byte(wc * 32 + fr, fq * 8);
;     ...
;     Unit cur, nxt; int ui = 0;
;     if (!S.next(0, cur)) return;
;     f32x4 acc[2][2][4][2];
; #pragma unroll
;     for (int a = 0; a < 2; ++a)
; #pragma unroll
;         for (int b = 0; b < 2; ++b)
; #pragma unroll
;             for (int m = 0; m < 4; ++m)
; #pragma unroll
;                 for (int n = 0; n < 2; ++n) acc[a][b][m][n] = (f32x4){0.f, 0.f, 0.f, 0.f};
;     bf16x8 At[4][2], B0[2][2], B1[2][2];
;     const char* cA = (const char*)g.A + (size_t)cur.pm * tstepA; const char* cB = (const char*)g.Bt + (size_t)cur.pn * tstep;
;     PG8_STAGE(PG8_SB(0, 0), cB, voffB); PG8_STAGE(PG8_SB(0, 1), cB + hstep, voffB); PG8_STAGE(PG8_SA(0, 0), cA, voffA); PG8_STAGE(PG8_SA(0, 1), cA + hstepA, voffA);
;     P(S);
;     if (wr == 1) PG8_BAR;
;     PG8_WAIT_V(2); PG8_BAR;
;     PG8_STAGE(PG8_SB(1, 0), cB + kstep, voffB); PG8_STAGE(PG8_SA(1, 0), cA + kstepA, voffA); PG8_STAGE(PG8_SB(1, 1), cB + hstep + kstep, voffB);
;     PG8_WAIT_V(6); PG8_BAR;
; __global__ void __launch_bounds__(NTHR, 2) fwd_megakernel(Args a_unused) {
;     ...
;                 {
;                     KArgs ka = kargs(); unsigned char* ws = ka->ws; unsigned char* wl = ws + (size_t)l * WL_SIZE;
.LBB0_840:
	s_or_b64 exec, exec, s[0:1]
	s_mov_b64 s[0:1], s[40:41]
	v_mov_b32_e32 v15, v234
	s_waitcnt lgkmcnt(0)
	s_barrier
	s_and_b64 vcc, exec, s[6:7]
	v_readfirstlane_b32 s26, v15
	s_cbranch_vccnz .LBB0_888
	v_lshlrev_b32_e32 v2, 4, v15
	v_add_u32_e32 v3, 0x2000, v2
	v_ashrrev_i32_e32 v0, 31, v3
	v_lshrrev_b32_e32 v0, 22, v0
	v_add_u32_e32 v0, v3, v0
	v_ashrrev_i32_e32 v0, 10, v0
	v_mul_i32_i24_e32 v4, 0x400, v0
	v_sub_u32_e32 v3, v3, v4
	v_lshrrev_b32_e32 v4, 4, v3
	v_bitop3_b32 v3, v4, v3, 32 bitop3:0x6c
	v_ashrrev_i32_e32 v4, 31, v3
	v_lshrrev_b32_e32 v4, 26, v4
	v_add_u32_e32 v4, v3, v4
	v_lshlrev_b32_e32 v5, 3, v0
	v_ashrrev_i32_e32 v10, 6, v4
	v_and_b32_e32 v5, -16, v5
	v_add_u32_e32 v5, v10, v5
	v_and_b32_e32 v6, 3, v10
	s_mov_b32 s6, 0x1fffe0
	v_lshrrev_b32_e32 v7, 2, v5
	v_lshlrev_b32_e32 v8, 1, v5
	v_and_or_b32 v6, v5, s6, v6
	v_and_b32_e32 v7, 4, v7
	v_and_b32_e32 v8, 24, v8
	v_and_b32_e32 v4, 0xc0, v4
	v_or3_b32 v6, v6, v7, v8
	v_sub_u32_e32 v3, v3, v4
	v_mov_b32_e32 v8, 1
	v_lshlrev_b32_e32 v7, 5, v0
	v_ashrrev_i16_sdwa v3, v8, sext(v3) dst_sel:DWORD dst_unused:UNUSED_PAD src0_sel:DWORD src1_sel:BYTE_0
	v_and_b32_e32 v7, 32, v7
	v_bfe_i32 v11, v3, 0, 16
	v_add_lshl_u32 v3, v7, v11, 1
	v_lshl_add_u32 v156, v6, 11, v3
	v_lshl_add_u32 v158, v5, 11, v3
	v_bfe_i32 v3, v15, 27, 1
	s_mov_b64 s[16:17], s[100:101]
	v_lshrrev_b32_e32 v3, 22, v3
	v_add_u32_e32 v3, v2, v3
	v_and_b32_e32 v3, 0xfffffc00, v3
	v_sub_u32_e32 v2, v2, v3
	v_readlane_b32 s0, v254, 20
	v_lshrrev_b32_e32 v3, 4, v2
	v_ashrrev_i32_e32 v4, 31, v15
	s_waitcnt lgkmcnt(0)
	s_add_u32 s0, s16, s0
	v_readlane_b32 s1, v254, 22
	v_bitop3_b32 v2, v3, v2, 32 bitop3:0x6c
	v_lshrrev_b32_e32 v4, 26, v4
	s_addc_u32 s1, s17, s1
	v_ashrrev_i32_e32 v3, 31, v2
	v_add_u32_e32 v4, v15, v4
	s_add_u32 s20, s16, 0x17b94000
	v_lshrrev_b32_e32 v3, 26, v3
	v_ashrrev_i32_e32 v13, 6, v4
	s_addc_u32 s24, s17, 0
	v_add_u32_e32 v3, v2, v3
	v_lshlrev_b32_e32 v4, 3, v13
	s_add_u32 s25, s0, 0x1500000
	v_ashrrev_i32_e32 v12, 6, v3
	v_and_b32_e32 v4, -16, v4
	s_addc_u32 s30, s1, 0
	v_add_u32_e32 v4, v12, v4
	s_add_u32 s0, s16, 0x12b10000
	v_and_b32_e32 v5, 3, v12
	v_lshrrev_b32_e32 v6, 2, v4
	v_lshlrev_b32_e32 v7, 1, v4
	v_and_b32_e32 v3, 0xc0, v3
	s_addc_u32 s1, s17, 0
	s_ashr_i32 s27, s26, 6
	v_and_or_b32 v5, v4, s6, v5
	v_and_b32_e32 v6, 4, v6
	v_and_b32_e32 v7, 24, v7
	v_sub_u32_e32 v2, v2, v3
	s_lshl_b32 s31, s27, 10
	v_or3_b32 v5, v5, v6, v7
	v_lshlrev_b32_e32 v6, 5, v13
	v_ashrrev_i16_sdwa v2, v8, sext(v2) dst_sel:DWORD dst_unused:UNUSED_PAD src0_sel:DWORD src1_sel:BYTE_0
	v_readlane_b32 s6, v254, 58
	v_and_b32_e32 v6, 32, v6
	v_bfe_i32 v14, v2, 0, 16
	v_readlane_b32 s7, v254, 59
	s_add_u32 s54, s25, s6
	v_add_lshl_u32 v2, v6, v14, 1
	s_addc_u32 s55, s30, s7
	s_add_i32 s38, s31, 0
	v_lshl_add_u32 v160, v5, 11, v2
	s_add_i32 m0, s38, 0x10000
	v_lshl_add_u32 v162, v4, 11, v2
	global_load_lds_dwordx4 v160, s[54:55]
	s_add_i32 m0, s38, 0x12000
	s_add_u32 s6, s54, 0x40000
	global_load_lds_dwordx4 v156, s[54:55]
	s_addc_u32 s7, s55, 0
	s_add_i32 m0, s38, 0x14000
	v_mov_b32_e32 v161, v1
	global_load_lds_dwordx4 v160, s[6:7]
	s_add_i32 m0, s38, 0x16000
	v_mov_b32_e32 v157, v1
	global_load_lds_dwordx4 v156, s[6:7]
	v_readlane_b32 s6, v254, 56
	v_readlane_b32 s7, v254, 57
	s_add_u32 s8, s20, s6
	s_addc_u32 s9, s24, s7
	s_add_i32 s48, s38, 0x2000
	s_mov_b32 m0, s38
	s_add_u32 s6, s8, 0x40000
	global_load_lds_dwordx4 v162, s[8:9]
	s_mov_b32 m0, s48
	s_addc_u32 s7, s9, 0
	s_add_i32 s49, s38, 0x4000
	global_load_lds_dwordx4 v158, s[8:9]
	s_mov_b32 m0, s49
	s_add_i32 s53, s38, 0x6000
	global_load_lds_dwordx4 v162, s[6:7]
	s_mov_b32 m0, s53
	v_mov_b32_e32 v163, v1
	global_load_lds_dwordx4 v158, s[6:7]
	v_mov_b32_e32 v159, v1
	v_mov_b32_e32 v16, v234
	s_movk_i32 s6, 0x100
	v_readlane_b32 s10, v254, 12
	v_lshl_add_u64 v[8:9], s[54:55], 0, v[160:161]
	v_lshl_add_u64 v[6:7], s[54:55], 0, v[156:157]
	v_lshl_add_u64 v[4:5], s[8:9], 0, v[162:163]
	v_lshl_add_u64 v[2:3], s[8:9], 0, v[158:159]
	s_movk_i32 s28, 0xc400
	v_cmp_gt_i32_e64 s[6:7], s6, v16
	v_lshl_add_u32 v17, v16, 2, s10
	s_mov_b64 s[10:11], s[2:3]
	s_branch .LBB0_844

; #define LAS __attribute__((address_space(3)))
; __device__ __forceinline__ unsigned xb_add(unsigned* p, unsigned v) { return __hip_atomic_fetch_add(p, v, __ATOMIC_RELAXED, __HIP_MEMORY_SCOPE_AGENT); }
; __device__ __forceinline__ unsigned xb_xcc_id() { return (unsigned)__builtin_amdgcn_s_getreg((3 << 11) | 20) & 0xFu; }
; __device__ __forceinline__ void xcd_barrier(unsigned* bar, volatile LAS unsigned* st) {
;     asm volatile("s_waitcnt vmcnt(0)" ::: "memory");
;     __syncthreads();
;     if (threadIdx.x == 0) {
;         const unsigned x = xb_xcc_id();
;         __builtin_amdgcn_s_waitcnt(0);
;         unsigned nloc = st[0], nx = st[1];
;         if (nloc == 0u) { xcd_barrier_complete(bar, x, nloc, nx); st[0] = nloc; st[1] = nx; }
;         const unsigned old = xb_add(&bar[XB_XSUB(x)], 1u);
.LBB0_888:
	s_mov_b64 s[6:7], s[40:41]
	s_waitcnt vmcnt(0)
	s_waitcnt lgkmcnt(0)
	s_barrier
	s_and_saveexec_b64 s[0:1], s[4:5]
	s_cbranch_execz .LBB0_195
	v_readlane_b32 s9, v254, 26
	s_mov_b64 s[6:7], s[100:101]
	s_getreg_b32 s8, hwreg(HW_REG_XCC_ID, 0, 4)
	v_mov_b32_e32 v0, s9
	s_waitcnt vmcnt(0) expcnt(0) lgkmcnt(0)
	ds_read_b32 v3, v0
	v_readlane_b32 s9, v254, 24
	s_and_b32 s20, s8, 15
	s_waitcnt lgkmcnt(0)
	v_cmp_ne_u32_e32 vcc, 0, v3
	v_mov_b32_e32 v0, s9
	ds_read_b32 v2, v0
	s_cbranch_vccnz .LBB0_904
	s_add_u32 s8, s6, 0x12b90200
	s_addc_u32 s9, s7, 0
	s_add_u32 s10, s6, 0x12b90400
	s_addc_u32 s11, s7, 0
	s_add_u32 s16, s6, 0x12b90500
	s_addc_u32 s17, s7, 0
	s_add_u32 s26, s6, 0x12b90600
	s_addc_u32 s27, s7, 0
	s_add_u32 s28, s6, 0x12b90700
	s_addc_u32 s29, s7, 0
	s_add_u32 s42, s6, 0x12b90800
	s_addc_u32 s43, s7, 0
	s_add_u32 s44, s6, 0x12b90900
	s_addc_u32 s45, s7, 0
	s_add_u32 s46, s6, 0x12b90a00
	s_addc_u32 s47, s7, 0
	s_add_u32 s54, s6, 0x12b90b00
	s_addc_u32 s55, s7, 0
	s_add_u32 s56, s6, 0x12b90c00
	s_addc_u32 s57, s7, 0
	s_add_u32 s58, s6, 0x12b90d00
	s_addc_u32 s59, s7, 0
	s_add_u32 s60, s6, 0x12b90e00
	s_addc_u32 s61, s7, 0
	s_add_u32 s70, s6, 0x12b90f00
	s_addc_u32 s71, s7, 0
	s_add_u32 s78, s6, 0x12b91000
	s_addc_u32 s79, s7, 0
	s_add_u32 s30, s6, 0x12b91100
	s_addc_u32 s31, s7, 0
	s_add_u32 s76, s6, 0x12b91200
	s_addc_u32 s77, s7, 0
	s_add_u32 s12, s6, 0x12b91300
	s_addc_u32 s13, s7, 0
	s_mov_b32 s24, 1
	s_branch .LBB0_892
